# GEMM staging: 79 LDS-DMA sites use SGPR base + 32-bit VGPR offset instead of a v_lshl_add_u64-built 64-bit address (s_nop 0 where the add was the m0 hazard filler)
# baseline (speedup 1.0000x reference)
.LBB0_262:
	s_and_b32 s4, s4, 3
	s_add_i32 m0, s1, 0x18000
	v_lshl_add_u64 v[6:7], v[6:7], 0, s[82:83]
	s_lshl_b32 s17, s5, 13
	s_lshl_b32 s38, s4, 5
	s_lshl_b32 s20, s4, 12
	s_waitcnt vmcnt(2)
	s_barrier
	global_load_lds_dwordx4 v[6:7], off
	v_lshl_add_u64 v[4:5], v[4:5], 0, s[82:83]
	s_add_i32 m0, s1, 0x1a000
	s_add_i32 s49, s1, 0x8000
	s_add_i32 s61, s1, 0xa000
	global_load_lds_dwordx4 v[4:5], off
	v_lshl_add_u64 v[0:1], v[0:1], 0, s[82:83]
	s_mov_b32 m0, s49
	s_add_u32 s18, s36, 0x80080
	global_load_lds_dwordx4 v[0:1], off
	v_lshl_add_u64 v[0:1], v[2:3], 0, s[82:83]
	s_mov_b32 m0, s61
	s_addc_u32 s19, s37, 0
	global_load_lds_dwordx4 v[0:1], off
	s_add_i32 m0, s1, 0x1c000
	s_nop 0
	global_load_lds_dwordx4 v132, s[18:19]
	s_add_i32 m0, s1, 0x1e000
	s_cmpk_lt_u32 s16, 0x100
	global_load_lds_dwordx4 v136, s[18:19]
	v_lshrrev_b32_e32 v1, 1, v8
	v_and_b32_e32 v140, 24, v1
	v_and_b32_e32 v0, 15, v8
	v_lshlrev_b32_e32 v1, 1, v140
	v_lshl_or_b32 v138, s5, 6, v0
	v_lshl_or_b32 v0, v0, 6, v1
	v_lshlrev_b32_e32 v1, 2, v8
	v_and_b32_e32 v1, 32, v1
	v_bitop3_b32 v2, v0, s17, v1 bitop3:0xde
	v_bitop3_b32 v141, v0, s20, v1 bitop3:0xde
	v_lshlrev_b32_e32 v0, 15, v9
	s_cselect_b64 s[16:17], -1, 0
	s_cmp_eq_u32 s4, 0
	v_and_b32_e32 v0, 0xffff0000, v0
	s_cselect_b64 s[18:19], -1, 0
	s_bfe_i64 s[20:21], s[92:93], 0x200000
	v_lshl_add_u32 v0, v10, 12, v0
	v_and_b32_e32 v1, 1, v9
	s_add_u32 s67, s8, 0x6000000
	v_lshl_or_b32 v0, v1, 6, v0
	s_addc_u32 s68, s9, 0
	v_lshl_add_u32 v146, v11, 1, v0
	v_lshlrev_b32_e32 v0, 15, v12
	s_add_u32 s69, s8, 0x3cf00000
	v_and_b32_e32 v0, 0xffff0000, v0
	s_waitcnt vmcnt(6)
	s_addc_u32 s70, s9, 0
	v_lshl_add_u32 v0, v13, 12, v0
	v_and_b32_e32 v1, 1, v12
	v_ashrrev_i32_e32 v139, 31, v138
	s_add_u32 s52, s8, 0x12b00000
	v_lshl_or_b32 v0, v1, 6, v0
	v_or_b32_e32 v142, s38, v140
	v_lshlrev_b64 v[144:145], 13, v[138:139]
	s_mov_b32 s66, 0
	s_addc_u32 s53, s9, 0
	v_mov_b32_e32 v147, v97
	v_lshl_add_u32 v148, v14, 1, v0
	v_mov_b32_e32 v149, v97
	v_add_u32_e32 v139, 0, v2
	s_lshl_b32 s54, s38, 1
	s_mov_b64 s[64:65], s[36:37]
	s_mov_b64 s[58:59], s[6:7]
	s_mov_b32 s51, 0x120000
	s_mov_b32 s80, 0x60000
	s_barrier
	s_branch .LBB0_265

.LBB0_282:
	s_add_i32 s44, s38, 2
	s_add_u32 s36, s6, 0xfff80080
	s_addc_u32 s37, s7, -1
	s_add_i32 s45, 0, 0x10000
	s_cmp_eq_u32 s41, s38
	s_cselect_b32 s39, s59, s37
	s_cselect_b32 s38, s58, s36
	v_add_u32_e32 v96, s45, v141
	s_cselect_b32 s37, s65, s43
	s_cselect_b32 s36, s64, s42
	s_add_i32 s50, 0, 0x14000
	ds_read_b128 v[150:153], v96
	ds_read_b128 v[154:157], v96 offset:1024
	ds_read_b128 v[158:161], v96 offset:2048
	ds_read_b128 v[162:165], v96 offset:3072
	v_add_u32_e32 v96, s50, v141
	ds_read_b128 v[166:169], v96
	ds_read_b128 v[170:173], v96 offset:1024
	ds_read_b128 v[174:177], v96 offset:2048
	ds_read_b128 v[178:181], v96 offset:3072
	s_add_i32 m0, s1, 0xc000
	ds_read_b128 v[182:185], v139
	ds_read_b128 v[186:189], v139 offset:1024
	ds_read_b128 v[190:193], v139 offset:2048
	ds_read_b128 v[204:207], v139 offset:3072
	ds_read_b128 v[208:211], v139 offset:4096
	ds_read_b128 v[212:215], v139 offset:5120
	ds_read_b128 v[216:219], v139 offset:6144
	ds_read_b128 v[220:223], v139 offset:7168
	global_load_lds_dwordx4 v146, s[6:7]
	s_add_i32 m0, s1, 0xe000
	s_nop 0
	global_load_lds_dwordx4 v148, s[6:7]
	s_waitcnt vmcnt(8) lgkmcnt(0)
	s_barrier
	s_setprio 1
	v_mfma_f32_16x16x32_bf16 v[126:129], v[150:153], v[182:185], v[126:129]
	v_mfma_f32_16x16x32_bf16 v[122:125], v[158:161], v[182:185], v[122:125]
	v_mfma_f32_16x16x32_bf16 v[118:121], v[150:153], v[190:193], v[118:121]
	v_mfma_f32_16x16x32_bf16 v[110:113], v[158:161], v[190:193], v[110:113]
	v_mfma_f32_16x16x32_bf16 v[102:105], v[150:153], v[208:211], v[102:105]
	v_mfma_f32_16x16x32_bf16 v[92:95], v[158:161], v[208:211], v[92:95]
	v_mfma_f32_16x16x32_bf16 v[84:87], v[150:153], v[216:219], v[84:87]
	v_mfma_f32_16x16x32_bf16 v[76:79], v[158:161], v[216:219], v[76:79]
	v_mfma_f32_16x16x32_bf16 v[126:129], v[154:157], v[186:189], v[126:129]
	v_mfma_f32_16x16x32_bf16 v[122:125], v[162:165], v[186:189], v[122:125]
	v_mfma_f32_16x16x32_bf16 v[118:121], v[154:157], v[204:207], v[118:121]
	v_mfma_f32_16x16x32_bf16 v[110:113], v[162:165], v[204:207], v[110:113]
	v_mfma_f32_16x16x32_bf16 v[102:105], v[154:157], v[212:215], v[102:105]
	v_mfma_f32_16x16x32_bf16 v[92:95], v[162:165], v[212:215], v[92:95]
	v_mfma_f32_16x16x32_bf16 v[84:87], v[154:157], v[220:223], v[84:87]
	v_mfma_f32_16x16x32_bf16 v[76:79], v[162:165], v[220:223], v[76:79]
	v_mfma_f32_16x16x32_bf16 v[114:117], v[166:169], v[182:185], v[114:117]
	v_mfma_f32_16x16x32_bf16 v[106:109], v[174:177], v[182:185], v[106:109]
	v_mfma_f32_16x16x32_bf16 v[98:101], v[166:169], v[190:193], v[98:101]
	v_mfma_f32_16x16x32_bf16 v[88:91], v[174:177], v[190:193], v[88:91]
	v_mfma_f32_16x16x32_bf16 v[80:83], v[166:169], v[208:211], v[80:83]
	v_mfma_f32_16x16x32_bf16 v[72:75], v[174:177], v[208:211], v[72:75]
	v_mfma_f32_16x16x32_bf16 v[68:71], v[166:169], v[216:219], v[68:71]
	v_mfma_f32_16x16x32_bf16 v[64:67], v[174:177], v[216:219], v[64:67]
	v_mfma_f32_16x16x32_bf16 v[114:117], v[170:173], v[186:189], v[114:117]
	v_mfma_f32_16x16x32_bf16 v[106:109], v[178:181], v[186:189], v[106:109]
	v_mfma_f32_16x16x32_bf16 v[98:101], v[170:173], v[204:207], v[98:101]
	v_mfma_f32_16x16x32_bf16 v[88:91], v[178:181], v[204:207], v[88:91]
	v_mfma_f32_16x16x32_bf16 v[80:83], v[170:173], v[212:215], v[80:83]
	v_mfma_f32_16x16x32_bf16 v[72:75], v[178:181], v[212:215], v[72:75]
	v_mfma_f32_16x16x32_bf16 v[68:71], v[170:173], v[220:223], v[68:71]
	v_mfma_f32_16x16x32_bf16 v[64:67], v[178:181], v[220:223], v[64:67]
	s_setprio 0
	s_barrier
	s_add_i32 s45, s45, s0
	v_lshl_add_u64 v[196:197], s[36:37], 0, v[132:133]
	s_mov_b32 m0, s45
	ds_read_b128 v[182:185], v139 offset:16384
	ds_read_b128 v[186:189], v139 offset:17408
	ds_read_b128 v[190:193], v139 offset:18432
	ds_read_b128 v[204:207], v139 offset:19456
	ds_read_b128 v[208:211], v139 offset:20480
	ds_read_b128 v[212:215], v139 offset:21504
	ds_read_b128 v[216:219], v139 offset:22528
	ds_read_b128 v[220:223], v139 offset:23552
	global_load_lds_dwordx4 v[196:197], off
	s_add_i32 m0, s45, 0x2000
	s_add_u32 s46, s36, 0x80000
	v_lshl_add_u64 v[198:199], s[36:37], 0, v[136:137]
	s_addc_u32 s47, s37, 0
	s_add_i32 s45, s50, s0
	global_load_lds_dwordx4 v[198:199], off
	s_mov_b32 m0, s45
	v_lshl_add_u64 v[202:203], s[38:39], 0, v[134:135]
	global_load_lds_dwordx4 v132, s[46:47]
	s_add_i32 m0, s45, 0x2000
	s_nop 0
	global_load_lds_dwordx4 v136, s[46:47]
	s_mov_b32 m0, s1
	v_lshl_add_u64 v[200:201], s[38:39], 0, v[130:131]
	global_load_lds_dwordx4 v[200:201], off
	s_mov_b32 m0, s15
	s_nop 0
	global_load_lds_dwordx4 v[202:203], off
	s_waitcnt vmcnt(8) lgkmcnt(0)
	s_barrier
	s_setprio 1
	v_mfma_f32_16x16x32_bf16 v[60:63], v[150:153], v[182:185], v[60:63]
	v_mfma_f32_16x16x32_bf16 v[56:59], v[158:161], v[182:185], v[56:59]
	v_mfma_f32_16x16x32_bf16 v[52:55], v[150:153], v[190:193], v[52:55]
	v_mfma_f32_16x16x32_bf16 v[44:47], v[158:161], v[190:193], v[44:47]
	v_mfma_f32_16x16x32_bf16 v[36:39], v[150:153], v[208:211], v[36:39]
	v_mfma_f32_16x16x32_bf16 v[28:31], v[158:161], v[208:211], v[28:31]
	v_mfma_f32_16x16x32_bf16 v[20:23], v[150:153], v[216:219], v[20:23]
	v_mfma_f32_16x16x32_bf16 v[12:15], v[158:161], v[216:219], v[12:15]
	v_mfma_f32_16x16x32_bf16 v[60:63], v[154:157], v[186:189], v[60:63]
	v_mfma_f32_16x16x32_bf16 v[56:59], v[162:165], v[186:189], v[56:59]
	v_mfma_f32_16x16x32_bf16 v[52:55], v[154:157], v[204:207], v[52:55]
	v_mfma_f32_16x16x32_bf16 v[44:47], v[162:165], v[204:207], v[44:47]
	v_mfma_f32_16x16x32_bf16 v[36:39], v[154:157], v[212:215], v[36:39]
	v_mfma_f32_16x16x32_bf16 v[28:31], v[162:165], v[212:215], v[28:31]
	v_mfma_f32_16x16x32_bf16 v[20:23], v[154:157], v[220:223], v[20:23]
	v_mfma_f32_16x16x32_bf16 v[12:15], v[162:165], v[220:223], v[12:15]
	v_mfma_f32_16x16x32_bf16 v[48:51], v[166:169], v[182:185], v[48:51]
	v_mfma_f32_16x16x32_bf16 v[40:43], v[174:177], v[182:185], v[40:43]
	v_mfma_f32_16x16x32_bf16 v[32:35], v[166:169], v[190:193], v[32:35]
	v_mfma_f32_16x16x32_bf16 v[24:27], v[174:177], v[190:193], v[24:27]
	v_mfma_f32_16x16x32_bf16 v[16:19], v[166:169], v[208:211], v[16:19]
	v_mfma_f32_16x16x32_bf16 v[8:11], v[174:177], v[208:211], v[8:11]
	v_mfma_f32_16x16x32_bf16 v[4:7], v[166:169], v[216:219], v[4:7]
	v_mfma_f32_16x16x32_bf16 v[0:3], v[174:177], v[216:219], v[0:3]
	v_mfma_f32_16x16x32_bf16 v[48:51], v[170:173], v[186:189], v[48:51]
	v_mfma_f32_16x16x32_bf16 v[40:43], v[178:181], v[186:189], v[40:43]
	v_mfma_f32_16x16x32_bf16 v[32:35], v[170:173], v[204:207], v[32:35]
	v_mfma_f32_16x16x32_bf16 v[24:27], v[178:181], v[204:207], v[24:27]
	v_mfma_f32_16x16x32_bf16 v[16:19], v[170:173], v[212:215], v[16:19]
	v_mfma_f32_16x16x32_bf16 v[8:11], v[178:181], v[212:215], v[8:11]
	v_mfma_f32_16x16x32_bf16 v[4:7], v[170:173], v[220:223], v[4:7]
	v_mfma_f32_16x16x32_bf16 v[0:3], v[178:181], v[220:223], v[0:3]
	s_setprio 0
	s_barrier
	s_add_i32 s45, 0, 0x18000
	v_add_u32_e32 v96, s45, v141
	s_add_i32 s46, 0, 0x1c000
	ds_read_b128 v[150:153], v96
	ds_read_b128 v[154:157], v96 offset:1024
	ds_read_b128 v[158:161], v96 offset:2048
	ds_read_b128 v[162:165], v96 offset:3072
	v_add_u32_e32 v96, s46, v141
	ds_read_b128 v[166:169], v96
	ds_read_b128 v[170:173], v96 offset:1024
	ds_read_b128 v[174:177], v96 offset:2048
	ds_read_b128 v[178:181], v96 offset:3072
	s_add_u32 s38, s38, 0x80000
	s_addc_u32 s39, s39, 0
	s_mov_b32 m0, s23
	ds_read_b128 v[182:185], v139 offset:32768
	ds_read_b128 v[186:189], v139 offset:33792
	ds_read_b128 v[190:193], v139 offset:34816
	ds_read_b128 v[204:207], v139 offset:35840
	ds_read_b128 v[208:211], v139 offset:36864
	ds_read_b128 v[212:215], v139 offset:37888
	ds_read_b128 v[216:219], v139 offset:38912
	ds_read_b128 v[220:223], v139 offset:39936
	global_load_lds_dwordx4 v130, s[38:39]
	s_mov_b32 m0, s48
	s_nop 0
	global_load_lds_dwordx4 v134, s[38:39]
	s_waitcnt vmcnt(8) lgkmcnt(0)
	s_barrier
	s_setprio 1
	v_mfma_f32_16x16x32_bf16 v[126:129], v[150:153], v[182:185], v[126:129]
	v_mfma_f32_16x16x32_bf16 v[122:125], v[158:161], v[182:185], v[122:125]
	v_mfma_f32_16x16x32_bf16 v[118:121], v[150:153], v[190:193], v[118:121]
	v_mfma_f32_16x16x32_bf16 v[110:113], v[158:161], v[190:193], v[110:113]
	v_mfma_f32_16x16x32_bf16 v[102:105], v[150:153], v[208:211], v[102:105]
	v_mfma_f32_16x16x32_bf16 v[92:95], v[158:161], v[208:211], v[92:95]
	v_mfma_f32_16x16x32_bf16 v[84:87], v[150:153], v[216:219], v[84:87]
	v_mfma_f32_16x16x32_bf16 v[76:79], v[158:161], v[216:219], v[76:79]
	v_mfma_f32_16x16x32_bf16 v[126:129], v[154:157], v[186:189], v[126:129]
	v_mfma_f32_16x16x32_bf16 v[122:125], v[162:165], v[186:189], v[122:125]
	v_mfma_f32_16x16x32_bf16 v[118:121], v[154:157], v[204:207], v[118:121]
	v_mfma_f32_16x16x32_bf16 v[110:113], v[162:165], v[204:207], v[110:113]
	v_mfma_f32_16x16x32_bf16 v[102:105], v[154:157], v[212:215], v[102:105]
	v_mfma_f32_16x16x32_bf16 v[92:95], v[162:165], v[212:215], v[92:95]
	v_mfma_f32_16x16x32_bf16 v[84:87], v[154:157], v[220:223], v[84:87]
	v_mfma_f32_16x16x32_bf16 v[76:79], v[162:165], v[220:223], v[76:79]
	v_mfma_f32_16x16x32_bf16 v[114:117], v[166:169], v[182:185], v[114:117]
	v_mfma_f32_16x16x32_bf16 v[106:109], v[174:177], v[182:185], v[106:109]
	v_mfma_f32_16x16x32_bf16 v[98:101], v[166:169], v[190:193], v[98:101]
	v_mfma_f32_16x16x32_bf16 v[88:91], v[174:177], v[190:193], v[88:91]
	v_mfma_f32_16x16x32_bf16 v[80:83], v[166:169], v[208:211], v[80:83]
	v_mfma_f32_16x16x32_bf16 v[72:75], v[174:177], v[208:211], v[72:75]
	v_mfma_f32_16x16x32_bf16 v[68:71], v[166:169], v[216:219], v[68:71]
	v_mfma_f32_16x16x32_bf16 v[64:67], v[174:177], v[216:219], v[64:67]
	v_mfma_f32_16x16x32_bf16 v[114:117], v[170:173], v[186:189], v[114:117]
	v_mfma_f32_16x16x32_bf16 v[106:109], v[178:181], v[186:189], v[106:109]
	v_mfma_f32_16x16x32_bf16 v[98:101], v[170:173], v[204:207], v[98:101]
	v_mfma_f32_16x16x32_bf16 v[88:91], v[178:181], v[204:207], v[88:91]
	v_mfma_f32_16x16x32_bf16 v[80:83], v[170:173], v[212:215], v[80:83]
	v_mfma_f32_16x16x32_bf16 v[72:75], v[178:181], v[212:215], v[72:75]
	v_mfma_f32_16x16x32_bf16 v[68:71], v[170:173], v[220:223], v[68:71]
	v_mfma_f32_16x16x32_bf16 v[64:67], v[178:181], v[220:223], v[64:67]
	s_setprio 0
	s_barrier
	s_add_i32 s38, s45, s0
	v_lshl_add_u64 v[196:197], v[196:197], 0, s[82:83]
	s_mov_b32 m0, s38
	ds_read_b128 v[182:185], v139 offset:49152
	ds_read_b128 v[186:189], v139 offset:50176
	ds_read_b128 v[190:193], v139 offset:51200
	ds_read_b128 v[204:207], v139 offset:52224
	ds_read_b128 v[208:211], v139 offset:53248
	ds_read_b128 v[212:215], v139 offset:54272
	ds_read_b128 v[216:219], v139 offset:55296
	ds_read_b128 v[220:223], v139 offset:56320
	global_load_lds_dwordx4 v[196:197], off
	s_add_i32 m0, s38, 0x2000
	s_add_u32 s36, s36, 0x80080
	v_lshl_add_u64 v[196:197], v[198:199], 0, s[82:83]
	s_addc_u32 s37, s37, 0
	s_add_i32 s38, s46, s0
	global_load_lds_dwordx4 v[196:197], off
	s_mov_b32 m0, s38
	s_nop 0
	global_load_lds_dwordx4 v132, s[36:37]
	s_add_i32 m0, s38, 0x2000
	s_nop 0
	global_load_lds_dwordx4 v136, s[36:37]
	s_mov_b32 m0, s49
	v_lshl_add_u64 v[196:197], v[200:201], 0, s[82:83]
	global_load_lds_dwordx4 v[196:197], off
	s_mov_b32 m0, s61
	v_lshl_add_u64 v[196:197], v[202:203], 0, s[82:83]
	global_load_lds_dwordx4 v[196:197], off
	s_waitcnt vmcnt(8) lgkmcnt(0)
	s_barrier
	s_setprio 1
	v_mfma_f32_16x16x32_bf16 v[60:63], v[150:153], v[182:185], v[60:63]
	v_mfma_f32_16x16x32_bf16 v[56:59], v[158:161], v[182:185], v[56:59]
	v_mfma_f32_16x16x32_bf16 v[52:55], v[150:153], v[190:193], v[52:55]
	v_mfma_f32_16x16x32_bf16 v[44:47], v[158:161], v[190:193], v[44:47]
	v_mfma_f32_16x16x32_bf16 v[36:39], v[150:153], v[208:211], v[36:39]
	v_mfma_f32_16x16x32_bf16 v[28:31], v[158:161], v[208:211], v[28:31]
	v_mfma_f32_16x16x32_bf16 v[20:23], v[150:153], v[216:219], v[20:23]
	v_mfma_f32_16x16x32_bf16 v[12:15], v[158:161], v[216:219], v[12:15]
	v_mfma_f32_16x16x32_bf16 v[60:63], v[154:157], v[186:189], v[60:63]
	v_mfma_f32_16x16x32_bf16 v[56:59], v[162:165], v[186:189], v[56:59]
	v_mfma_f32_16x16x32_bf16 v[52:55], v[154:157], v[204:207], v[52:55]
	v_mfma_f32_16x16x32_bf16 v[44:47], v[162:165], v[204:207], v[44:47]
	v_mfma_f32_16x16x32_bf16 v[36:39], v[154:157], v[212:215], v[36:39]
	v_mfma_f32_16x16x32_bf16 v[28:31], v[162:165], v[212:215], v[28:31]
	v_mfma_f32_16x16x32_bf16 v[20:23], v[154:157], v[220:223], v[20:23]
	v_mfma_f32_16x16x32_bf16 v[12:15], v[162:165], v[220:223], v[12:15]
	v_mfma_f32_16x16x32_bf16 v[48:51], v[166:169], v[182:185], v[48:51]
	v_mfma_f32_16x16x32_bf16 v[40:43], v[174:177], v[182:185], v[40:43]
	v_mfma_f32_16x16x32_bf16 v[32:35], v[166:169], v[190:193], v[32:35]
	v_mfma_f32_16x16x32_bf16 v[24:27], v[174:177], v[190:193], v[24:27]
	v_mfma_f32_16x16x32_bf16 v[16:19], v[166:169], v[208:211], v[16:19]
	v_mfma_f32_16x16x32_bf16 v[8:11], v[174:177], v[208:211], v[8:11]
	v_mfma_f32_16x16x32_bf16 v[4:7], v[166:169], v[216:219], v[4:7]
	v_mfma_f32_16x16x32_bf16 v[0:3], v[174:177], v[216:219], v[0:3]
	v_mfma_f32_16x16x32_bf16 v[48:51], v[170:173], v[186:189], v[48:51]
	v_mfma_f32_16x16x32_bf16 v[40:43], v[178:181], v[186:189], v[40:43]
	v_mfma_f32_16x16x32_bf16 v[32:35], v[170:173], v[204:207], v[32:35]
	v_mfma_f32_16x16x32_bf16 v[24:27], v[178:181], v[204:207], v[24:27]
	v_mfma_f32_16x16x32_bf16 v[16:19], v[170:173], v[212:215], v[16:19]
	v_mfma_f32_16x16x32_bf16 v[8:11], v[178:181], v[212:215], v[8:11]
	v_mfma_f32_16x16x32_bf16 v[4:7], v[170:173], v[220:223], v[4:7]
	v_mfma_f32_16x16x32_bf16 v[0:3], v[178:181], v[220:223], v[0:3]
	s_setprio 0
	s_barrier
	s_add_u32 s6, s6, 0x100
	s_addc_u32 s7, s7, 0
	s_add_u32 s42, s42, 0x100
	s_addc_u32 s43, s43, 0
	s_cmp_ge_i32 s44, s40
	s_mov_b32 s38, s44
	s_cbranch_scc0 .LBB0_282
	s_and_b64 vcc, exec, s[16:17]
	s_cbranch_vccz .LBB0_287
	s_barrier
	s_cmp_lg_u32 s55, 1
	s_mov_b64 s[6:7], -1
	s_cbranch_scc1 .LBB0_288

.LBB0_431:
	s_add_u32 s8, s4, 0x33f00000
	s_addc_u32 s9, s5, 0
	s_lshl_b32 s4, s12, 5
	s_and_b32 s12, s4, 0x60
	s_add_i32 m0, s38, 0x18000
	v_lshl_add_u64 v[6:7], v[6:7], 0, s[82:83]
	s_lshl_b32 s13, s11, 13
	s_lshl_b32 s14, s12, 7
	s_waitcnt vmcnt(2)
	s_barrier
	global_load_lds_dwordx4 v[6:7], off
	v_lshl_add_u64 v[4:5], v[4:5], 0, s[82:83]
	s_add_i32 m0, s38, 0x1a000
	s_add_i32 s42, s38, 0x8000
	s_add_i32 s43, s38, 0xa000
	global_load_lds_dwordx4 v[4:5], off
	v_lshl_add_u64 v[0:1], v[0:1], 0, s[82:83]
	s_mov_b32 m0, s42
	s_add_u32 s4, s22, 0x20080
	global_load_lds_dwordx4 v[0:1], off
	v_lshl_add_u64 v[0:1], v[2:3], 0, s[82:83]
	s_mov_b32 m0, s43
	s_addc_u32 s5, s23, 0
	global_load_lds_dwordx4 v[0:1], off
	s_add_i32 m0, s38, 0x1c000
	s_nop 0
	global_load_lds_dwordx4 v134, s[4:5]
	s_add_i32 m0, s38, 0x1e000
	s_cmpk_lt_u32 s10, 0x100
	global_load_lds_dwordx4 v130, s[4:5]
	v_lshrrev_b32_e32 v0, 1, v8
	v_and_b32_e32 v0, 24, v0
	v_and_b32_e32 v1, 15, v8
	v_lshlrev_b32_e32 v2, 1, v0
	v_lshl_or_b32 v144, s11, 6, v1
	v_lshl_or_b32 v1, v1, 6, v2
	v_lshlrev_b32_e32 v2, 2, v8
	v_and_b32_e32 v2, 32, v2
	v_bitop3_b32 v3, v1, s13, v2 bitop3:0xde
	v_bitop3_b32 v145, v1, s14, v2 bitop3:0xde
	v_lshlrev_b32_e32 v1, 13, v13
	v_and_b32_e32 v1, 0xffffc000, v1
	v_lshl_add_u32 v1, v12, 10, v1
	v_and_b32_e32 v2, 1, v13
	v_lshl_or_b32 v1, v2, 6, v1
	v_lshl_add_u32 v138, v14, 1, v1
	v_lshlrev_b32_e32 v1, 13, v9
	v_and_b32_e32 v1, 0xffffc000, v1
	s_waitcnt vmcnt(6)
	v_lshl_add_u32 v1, v10, 10, v1
	v_and_b32_e32 v2, 1, v9
	v_lshl_or_b32 v1, v2, 6, v1
	s_cselect_b64 s[10:11], -1, 0
	s_ashr_i32 s44, s0, 31
	v_mov_b32_e32 v139, v97
	v_lshl_add_u32 v140, v11, 1, v1
	v_mov_b32_e32 v141, v97
	s_mov_b32 s45, 0
	v_add_u32_e32 v146, 0, v3
	s_lshl_b32 s92, s12, 1
	v_lshlrev_b32_e32 v96, 1, v0
	s_mov_b64 s[16:17], s[22:23]
	s_mov_b64 s[14:15], s[20:21]
	s_barrier
	s_branch .LBB0_434

.LBB0_437:
	s_add_u32 s22, s20, 0xfffe0080
	s_addc_u32 s23, s21, -1
	s_add_i32 s46, 0, 0x10000
	s_cmp_eq_u32 s54, 4
	s_cselect_b32 s37, s15, s23
	s_cselect_b32 s36, s14, s22
	v_add_u32_e32 v142, s46, v145
	s_cselect_b32 s23, s17, s19
	s_cselect_b32 s22, s16, s13
	s_add_i32 s50, 0, 0x14000
	ds_read_b128 v[148:151], v142
	ds_read_b128 v[152:155], v142 offset:1024
	ds_read_b128 v[156:159], v142 offset:2048
	ds_read_b128 v[160:163], v142 offset:3072
	v_add_u32_e32 v142, s50, v145
	ds_read_b128 v[164:167], v142
	ds_read_b128 v[168:171], v142 offset:1024
	ds_read_b128 v[172:175], v142 offset:2048
	ds_read_b128 v[176:179], v142 offset:3072
	s_add_i32 m0, s38, 0xc000
	ds_read_b128 v[180:183], v146
	ds_read_b128 v[184:187], v146 offset:1024
	ds_read_b128 v[188:191], v146 offset:2048
	ds_read_b128 v[204:207], v146 offset:3072
	ds_read_b128 v[208:211], v146 offset:4096
	ds_read_b128 v[212:215], v146 offset:5120
	ds_read_b128 v[216:219], v146 offset:6144
	ds_read_b128 v[220:223], v146 offset:7168
	global_load_lds_dwordx4 v138, s[20:21]
	s_add_i32 m0, s38, 0xe000
	s_nop 0
	global_load_lds_dwordx4 v140, s[20:21]
	s_waitcnt vmcnt(8) lgkmcnt(0)
	s_barrier
	s_setprio 1
	v_mfma_f32_16x16x32_bf16 v[126:129], v[148:151], v[180:183], v[126:129]
	v_mfma_f32_16x16x32_bf16 v[122:125], v[156:159], v[180:183], v[122:125]
	v_mfma_f32_16x16x32_bf16 v[118:121], v[148:151], v[188:191], v[118:121]
	v_mfma_f32_16x16x32_bf16 v[110:113], v[156:159], v[188:191], v[110:113]
	v_mfma_f32_16x16x32_bf16 v[102:105], v[148:151], v[208:211], v[102:105]
	v_mfma_f32_16x16x32_bf16 v[92:95], v[156:159], v[208:211], v[92:95]
	v_mfma_f32_16x16x32_bf16 v[84:87], v[148:151], v[216:219], v[84:87]
	v_mfma_f32_16x16x32_bf16 v[76:79], v[156:159], v[216:219], v[76:79]
	v_mfma_f32_16x16x32_bf16 v[126:129], v[152:155], v[184:187], v[126:129]
	v_mfma_f32_16x16x32_bf16 v[122:125], v[160:163], v[184:187], v[122:125]
	v_mfma_f32_16x16x32_bf16 v[118:121], v[152:155], v[204:207], v[118:121]
	v_mfma_f32_16x16x32_bf16 v[110:113], v[160:163], v[204:207], v[110:113]
	v_mfma_f32_16x16x32_bf16 v[102:105], v[152:155], v[212:215], v[102:105]
	v_mfma_f32_16x16x32_bf16 v[92:95], v[160:163], v[212:215], v[92:95]
	v_mfma_f32_16x16x32_bf16 v[84:87], v[152:155], v[220:223], v[84:87]
	v_mfma_f32_16x16x32_bf16 v[76:79], v[160:163], v[220:223], v[76:79]
	v_mfma_f32_16x16x32_bf16 v[114:117], v[164:167], v[180:183], v[114:117]
	v_mfma_f32_16x16x32_bf16 v[106:109], v[172:175], v[180:183], v[106:109]
	v_mfma_f32_16x16x32_bf16 v[98:101], v[164:167], v[188:191], v[98:101]
	v_mfma_f32_16x16x32_bf16 v[88:91], v[172:175], v[188:191], v[88:91]
	v_mfma_f32_16x16x32_bf16 v[80:83], v[164:167], v[208:211], v[80:83]
	v_mfma_f32_16x16x32_bf16 v[72:75], v[172:175], v[208:211], v[72:75]
	v_mfma_f32_16x16x32_bf16 v[68:71], v[164:167], v[216:219], v[68:71]
	v_mfma_f32_16x16x32_bf16 v[64:67], v[172:175], v[216:219], v[64:67]
	v_mfma_f32_16x16x32_bf16 v[114:117], v[168:171], v[184:187], v[114:117]
	v_mfma_f32_16x16x32_bf16 v[106:109], v[176:179], v[184:187], v[106:109]
	v_mfma_f32_16x16x32_bf16 v[98:101], v[168:171], v[204:207], v[98:101]
	v_mfma_f32_16x16x32_bf16 v[88:91], v[176:179], v[204:207], v[88:91]
	v_mfma_f32_16x16x32_bf16 v[80:83], v[168:171], v[212:215], v[80:83]
	v_mfma_f32_16x16x32_bf16 v[72:75], v[176:179], v[212:215], v[72:75]
	v_mfma_f32_16x16x32_bf16 v[68:71], v[168:171], v[220:223], v[68:71]
	v_mfma_f32_16x16x32_bf16 v[64:67], v[176:179], v[220:223], v[64:67]
	s_setprio 0
	s_barrier
	s_add_i32 s46, s46, s31
	v_lshl_add_u64 v[142:143], s[22:23], 0, v[134:135]
	s_mov_b32 m0, s46
	ds_read_b128 v[180:183], v146 offset:16384
	ds_read_b128 v[184:187], v146 offset:17408
	ds_read_b128 v[188:191], v146 offset:18432
	ds_read_b128 v[204:207], v146 offset:19456
	ds_read_b128 v[208:211], v146 offset:20480
	ds_read_b128 v[212:215], v146 offset:21504
	ds_read_b128 v[216:219], v146 offset:22528
	ds_read_b128 v[220:223], v146 offset:23552
	global_load_lds_dwordx4 v[142:143], off
	s_add_i32 m0, s46, 0x2000
	s_add_u32 s46, s22, 0x20000
	v_lshl_add_u64 v[192:193], s[22:23], 0, v[130:131]
	s_addc_u32 s47, s23, 0
	s_add_i32 s50, s50, s31
	global_load_lds_dwordx4 v[192:193], off
	s_mov_b32 m0, s50
	v_lshl_add_u64 v[198:199], s[36:37], 0, v[132:133]
	global_load_lds_dwordx4 v134, s[46:47]
	s_add_i32 m0, s50, 0x2000
	s_nop 0
	global_load_lds_dwordx4 v130, s[46:47]
	s_mov_b32 m0, s38
	v_lshl_add_u64 v[196:197], s[36:37], 0, v[136:137]
	global_load_lds_dwordx4 v[196:197], off
	s_mov_b32 m0, s39
	s_nop 0
	global_load_lds_dwordx4 v[198:199], off
	s_waitcnt vmcnt(8) lgkmcnt(0)
	s_barrier
	s_setprio 1
	v_mfma_f32_16x16x32_bf16 v[60:63], v[148:151], v[180:183], v[60:63]
	v_mfma_f32_16x16x32_bf16 v[56:59], v[156:159], v[180:183], v[56:59]
	v_mfma_f32_16x16x32_bf16 v[52:55], v[148:151], v[188:191], v[52:55]
	v_mfma_f32_16x16x32_bf16 v[44:47], v[156:159], v[188:191], v[44:47]
	v_mfma_f32_16x16x32_bf16 v[36:39], v[148:151], v[208:211], v[36:39]
	v_mfma_f32_16x16x32_bf16 v[28:31], v[156:159], v[208:211], v[28:31]
	v_mfma_f32_16x16x32_bf16 v[20:23], v[148:151], v[216:219], v[20:23]
	v_mfma_f32_16x16x32_bf16 v[12:15], v[156:159], v[216:219], v[12:15]
	v_mfma_f32_16x16x32_bf16 v[60:63], v[152:155], v[184:187], v[60:63]
	v_mfma_f32_16x16x32_bf16 v[56:59], v[160:163], v[184:187], v[56:59]
	v_mfma_f32_16x16x32_bf16 v[52:55], v[152:155], v[204:207], v[52:55]
	v_mfma_f32_16x16x32_bf16 v[44:47], v[160:163], v[204:207], v[44:47]
	v_mfma_f32_16x16x32_bf16 v[36:39], v[152:155], v[212:215], v[36:39]
	v_mfma_f32_16x16x32_bf16 v[28:31], v[160:163], v[212:215], v[28:31]
	v_mfma_f32_16x16x32_bf16 v[20:23], v[152:155], v[220:223], v[20:23]
	v_mfma_f32_16x16x32_bf16 v[12:15], v[160:163], v[220:223], v[12:15]
	v_mfma_f32_16x16x32_bf16 v[48:51], v[164:167], v[180:183], v[48:51]
	v_mfma_f32_16x16x32_bf16 v[40:43], v[172:175], v[180:183], v[40:43]
	v_mfma_f32_16x16x32_bf16 v[32:35], v[164:167], v[188:191], v[32:35]
	v_mfma_f32_16x16x32_bf16 v[24:27], v[172:175], v[188:191], v[24:27]
	v_mfma_f32_16x16x32_bf16 v[16:19], v[164:167], v[208:211], v[16:19]
	v_mfma_f32_16x16x32_bf16 v[8:11], v[172:175], v[208:211], v[8:11]
	v_mfma_f32_16x16x32_bf16 v[4:7], v[164:167], v[216:219], v[4:7]
	v_mfma_f32_16x16x32_bf16 v[0:3], v[172:175], v[216:219], v[0:3]
	v_mfma_f32_16x16x32_bf16 v[48:51], v[168:171], v[184:187], v[48:51]
	v_mfma_f32_16x16x32_bf16 v[40:43], v[176:179], v[184:187], v[40:43]
	v_mfma_f32_16x16x32_bf16 v[32:35], v[168:171], v[204:207], v[32:35]
	v_mfma_f32_16x16x32_bf16 v[24:27], v[176:179], v[204:207], v[24:27]
	v_mfma_f32_16x16x32_bf16 v[16:19], v[168:171], v[212:215], v[16:19]
	v_mfma_f32_16x16x32_bf16 v[8:11], v[176:179], v[212:215], v[8:11]
	v_mfma_f32_16x16x32_bf16 v[4:7], v[168:171], v[220:223], v[4:7]
	v_mfma_f32_16x16x32_bf16 v[0:3], v[176:179], v[220:223], v[0:3]
	s_setprio 0
	s_barrier
	s_add_i32 s46, 0, 0x18000
	v_add_u32_e32 v147, s46, v145
	s_add_i32 s47, 0, 0x1c000
	ds_read_b128 v[148:151], v147
	ds_read_b128 v[152:155], v147 offset:1024
	ds_read_b128 v[156:159], v147 offset:2048
	ds_read_b128 v[160:163], v147 offset:3072
	v_add_u32_e32 v147, s47, v145
	ds_read_b128 v[164:167], v147
	ds_read_b128 v[168:171], v147 offset:1024
	ds_read_b128 v[172:175], v147 offset:2048
	ds_read_b128 v[176:179], v147 offset:3072
	s_add_u32 s36, s36, 0x20000
	s_addc_u32 s37, s37, 0
	s_mov_b32 m0, s40
	ds_read_b128 v[180:183], v146 offset:32768
	ds_read_b128 v[184:187], v146 offset:33792
	ds_read_b128 v[188:191], v146 offset:34816
	ds_read_b128 v[204:207], v146 offset:35840
	ds_read_b128 v[208:211], v146 offset:36864
	ds_read_b128 v[212:215], v146 offset:37888
	ds_read_b128 v[216:219], v146 offset:38912
	ds_read_b128 v[220:223], v146 offset:39936
	global_load_lds_dwordx4 v136, s[36:37]
	s_mov_b32 m0, s41
	s_nop 0
	global_load_lds_dwordx4 v132, s[36:37]
	s_waitcnt vmcnt(8) lgkmcnt(0)
	s_barrier
	s_setprio 1
	v_mfma_f32_16x16x32_bf16 v[126:129], v[148:151], v[180:183], v[126:129]
	v_mfma_f32_16x16x32_bf16 v[122:125], v[156:159], v[180:183], v[122:125]
	v_mfma_f32_16x16x32_bf16 v[118:121], v[148:151], v[188:191], v[118:121]
	v_mfma_f32_16x16x32_bf16 v[110:113], v[156:159], v[188:191], v[110:113]
	v_mfma_f32_16x16x32_bf16 v[102:105], v[148:151], v[208:211], v[102:105]
	v_mfma_f32_16x16x32_bf16 v[92:95], v[156:159], v[208:211], v[92:95]
	v_mfma_f32_16x16x32_bf16 v[84:87], v[148:151], v[216:219], v[84:87]
	v_mfma_f32_16x16x32_bf16 v[76:79], v[156:159], v[216:219], v[76:79]
	v_mfma_f32_16x16x32_bf16 v[126:129], v[152:155], v[184:187], v[126:129]
	v_mfma_f32_16x16x32_bf16 v[122:125], v[160:163], v[184:187], v[122:125]
	v_mfma_f32_16x16x32_bf16 v[118:121], v[152:155], v[204:207], v[118:121]
	v_mfma_f32_16x16x32_bf16 v[110:113], v[160:163], v[204:207], v[110:113]
	v_mfma_f32_16x16x32_bf16 v[102:105], v[152:155], v[212:215], v[102:105]
	v_mfma_f32_16x16x32_bf16 v[92:95], v[160:163], v[212:215], v[92:95]
	v_mfma_f32_16x16x32_bf16 v[84:87], v[152:155], v[220:223], v[84:87]
	v_mfma_f32_16x16x32_bf16 v[76:79], v[160:163], v[220:223], v[76:79]
	v_mfma_f32_16x16x32_bf16 v[114:117], v[164:167], v[180:183], v[114:117]
	v_mfma_f32_16x16x32_bf16 v[106:109], v[172:175], v[180:183], v[106:109]
	v_mfma_f32_16x16x32_bf16 v[98:101], v[164:167], v[188:191], v[98:101]
	v_mfma_f32_16x16x32_bf16 v[88:91], v[172:175], v[188:191], v[88:91]
	v_mfma_f32_16x16x32_bf16 v[80:83], v[164:167], v[208:211], v[80:83]
	v_mfma_f32_16x16x32_bf16 v[72:75], v[172:175], v[208:211], v[72:75]
	v_mfma_f32_16x16x32_bf16 v[68:71], v[164:167], v[216:219], v[68:71]
	v_mfma_f32_16x16x32_bf16 v[64:67], v[172:175], v[216:219], v[64:67]
	v_mfma_f32_16x16x32_bf16 v[114:117], v[168:171], v[184:187], v[114:117]
	v_mfma_f32_16x16x32_bf16 v[106:109], v[176:179], v[184:187], v[106:109]
	v_mfma_f32_16x16x32_bf16 v[98:101], v[168:171], v[204:207], v[98:101]
	v_mfma_f32_16x16x32_bf16 v[88:91], v[176:179], v[204:207], v[88:91]
	v_mfma_f32_16x16x32_bf16 v[80:83], v[168:171], v[212:215], v[80:83]
	v_mfma_f32_16x16x32_bf16 v[72:75], v[176:179], v[212:215], v[72:75]
	v_mfma_f32_16x16x32_bf16 v[68:71], v[168:171], v[220:223], v[68:71]
	v_mfma_f32_16x16x32_bf16 v[64:67], v[176:179], v[220:223], v[64:67]
	s_setprio 0
	s_barrier
	s_add_i32 s36, s46, s31
	v_lshl_add_u64 v[142:143], v[142:143], 0, s[82:83]
	s_mov_b32 m0, s36
	ds_read_b128 v[180:183], v146 offset:49152
	ds_read_b128 v[184:187], v146 offset:50176
	ds_read_b128 v[188:191], v146 offset:51200
	ds_read_b128 v[204:207], v146 offset:52224
	ds_read_b128 v[208:211], v146 offset:53248
	ds_read_b128 v[212:215], v146 offset:54272
	ds_read_b128 v[216:219], v146 offset:55296
	ds_read_b128 v[220:223], v146 offset:56320
	global_load_lds_dwordx4 v[142:143], off
	s_add_i32 m0, s36, 0x2000
	s_add_u32 s22, s22, 0x20080
	v_lshl_add_u64 v[142:143], v[192:193], 0, s[82:83]
	s_addc_u32 s23, s23, 0
	s_add_i32 s36, s47, s31
	global_load_lds_dwordx4 v[142:143], off
	s_mov_b32 m0, s36
	s_nop 0
	global_load_lds_dwordx4 v134, s[22:23]
	s_add_i32 m0, s36, 0x2000
	s_nop 0
	global_load_lds_dwordx4 v130, s[22:23]
	s_mov_b32 m0, s42
	v_lshl_add_u64 v[142:143], v[196:197], 0, s[82:83]
	global_load_lds_dwordx4 v[142:143], off
	s_mov_b32 m0, s43
	v_lshl_add_u64 v[142:143], v[198:199], 0, s[82:83]
	global_load_lds_dwordx4 v[142:143], off
	s_waitcnt vmcnt(8) lgkmcnt(0)
	s_barrier
	s_setprio 1
	v_mfma_f32_16x16x32_bf16 v[60:63], v[148:151], v[180:183], v[60:63]
	v_mfma_f32_16x16x32_bf16 v[56:59], v[156:159], v[180:183], v[56:59]
	v_mfma_f32_16x16x32_bf16 v[52:55], v[148:151], v[188:191], v[52:55]
	v_mfma_f32_16x16x32_bf16 v[44:47], v[156:159], v[188:191], v[44:47]
	v_mfma_f32_16x16x32_bf16 v[36:39], v[148:151], v[208:211], v[36:39]
	v_mfma_f32_16x16x32_bf16 v[28:31], v[156:159], v[208:211], v[28:31]
	v_mfma_f32_16x16x32_bf16 v[20:23], v[148:151], v[216:219], v[20:23]
	v_mfma_f32_16x16x32_bf16 v[12:15], v[156:159], v[216:219], v[12:15]
	v_mfma_f32_16x16x32_bf16 v[60:63], v[152:155], v[184:187], v[60:63]
	v_mfma_f32_16x16x32_bf16 v[56:59], v[160:163], v[184:187], v[56:59]
	v_mfma_f32_16x16x32_bf16 v[52:55], v[152:155], v[204:207], v[52:55]
	v_mfma_f32_16x16x32_bf16 v[44:47], v[160:163], v[204:207], v[44:47]
	v_mfma_f32_16x16x32_bf16 v[36:39], v[152:155], v[212:215], v[36:39]
	v_mfma_f32_16x16x32_bf16 v[28:31], v[160:163], v[212:215], v[28:31]
	v_mfma_f32_16x16x32_bf16 v[20:23], v[152:155], v[220:223], v[20:23]
	v_mfma_f32_16x16x32_bf16 v[12:15], v[160:163], v[220:223], v[12:15]
	v_mfma_f32_16x16x32_bf16 v[48:51], v[164:167], v[180:183], v[48:51]
	v_mfma_f32_16x16x32_bf16 v[40:43], v[172:175], v[180:183], v[40:43]
	v_mfma_f32_16x16x32_bf16 v[32:35], v[164:167], v[188:191], v[32:35]
	v_mfma_f32_16x16x32_bf16 v[24:27], v[172:175], v[188:191], v[24:27]
	v_mfma_f32_16x16x32_bf16 v[16:19], v[164:167], v[208:211], v[16:19]
	v_mfma_f32_16x16x32_bf16 v[8:11], v[172:175], v[208:211], v[8:11]
	v_mfma_f32_16x16x32_bf16 v[4:7], v[164:167], v[216:219], v[4:7]
	v_mfma_f32_16x16x32_bf16 v[0:3], v[172:175], v[216:219], v[0:3]
	v_mfma_f32_16x16x32_bf16 v[48:51], v[168:171], v[184:187], v[48:51]
	v_mfma_f32_16x16x32_bf16 v[40:43], v[176:179], v[184:187], v[40:43]
	v_mfma_f32_16x16x32_bf16 v[32:35], v[168:171], v[204:207], v[32:35]
	v_mfma_f32_16x16x32_bf16 v[24:27], v[176:179], v[204:207], v[24:27]
	v_mfma_f32_16x16x32_bf16 v[16:19], v[168:171], v[212:215], v[16:19]
	v_mfma_f32_16x16x32_bf16 v[8:11], v[176:179], v[212:215], v[8:11]
	v_mfma_f32_16x16x32_bf16 v[4:7], v[168:171], v[220:223], v[4:7]
	v_mfma_f32_16x16x32_bf16 v[0:3], v[176:179], v[220:223], v[0:3]
	s_setprio 0
	s_barrier
	s_add_i32 s54, s54, 2
	s_add_u32 s20, s20, 0x100
	s_addc_u32 s21, s21, 0
	s_add_u32 s13, s13, 0x100
	s_addc_u32 s19, s19, 0
	s_cmp_gt_u32 s54, 5
	s_cbranch_scc0 .LBB0_437
	s_and_b64 vcc, exec, s[10:11]
	s_cbranch_vccz .LBB0_440
	s_barrier

.LBB0_508:
	s_lshl_b32 s8, s8, 3
	s_or_b32 s8, s8, s14
	s_and_b32 s44, s0, 7
	s_add_i32 s45, s8, 32
	s_add_u32 s6, s6, 0x48f00000
	s_addc_u32 s7, s7, 0
	s_lshl_b32 s8, s12, 5
	s_and_b32 s12, s8, 0x60
	s_lshl_b32 s20, s11, 13
	s_lshl_b32 s21, s12, 7
	s_add_u32 s14, s9, 0x8080
	v_mov_b32_e32 v135, v97
	s_addc_u32 s15, s13, 0
	v_mov_b32_e32 v131, v97
	s_add_i32 m0, s31, 0x18000
	s_waitcnt vmcnt(2)
	s_barrier
	global_load_lds_dwordx4 v134, s[14:15]
	s_add_i32 m0, s31, 0x1a000
	s_add_i32 s39, s31, 0x8000
	s_add_i32 s40, s31, 0xa000
	global_load_lds_dwordx4 v130, s[14:15]
	v_lshl_add_u64 v[0:1], v[0:1], 0, s[82:83]
	s_mov_b32 m0, s39
	s_add_u32 s8, s9, 0x608080
	global_load_lds_dwordx4 v[0:1], off
	v_lshl_add_u64 v[0:1], v[2:3], 0, s[82:83]
	s_mov_b32 m0, s40
	s_addc_u32 s9, s13, 0
	global_load_lds_dwordx4 v[0:1], off
	s_add_i32 m0, s31, 0x1c000
	s_nop 0
	global_load_lds_dwordx4 v134, s[8:9]
	s_add_i32 m0, s31, 0x1e000
	s_cmpk_lt_u32 s10, 0x100
	global_load_lds_dwordx4 v130, s[8:9]
	v_lshrrev_b32_e32 v0, 1, v4
	v_and_b32_e32 v0, 24, v0
	v_and_b32_e32 v1, 15, v4
	v_lshlrev_b32_e32 v2, 1, v0
	v_lshl_or_b32 v144, s11, 6, v1
	v_lshl_or_b32 v1, v1, 6, v2
	v_lshlrev_b32_e32 v2, 2, v4
	v_and_b32_e32 v2, 32, v2
	v_bitop3_b32 v3, v1, s20, v2 bitop3:0xde
	v_bitop3_b32 v145, v1, s21, v2 bitop3:0xde
	v_lshlrev_b32_e32 v1, 16, v9
	v_and_b32_e32 v1, 0xfffe0000, v1
	v_lshl_add_u32 v1, v8, 13, v1
	v_and_b32_e32 v2, 1, v9
	v_lshl_or_b32 v1, v2, 6, v1
	v_lshl_add_u32 v138, v10, 1, v1
	v_lshlrev_b32_e32 v1, 16, v5
	v_and_b32_e32 v1, 0xfffe0000, v1
	s_waitcnt vmcnt(6)
	v_lshl_add_u32 v1, v6, 13, v1
	v_and_b32_e32 v2, 1, v5
	v_lshl_or_b32 v1, v2, 6, v1
	s_cselect_b64 s[8:9], -1, 0
	v_mov_b32_e32 v139, v97
	v_lshl_add_u32 v140, v7, 1, v1
	v_mov_b32_e32 v141, v97
	s_mov_b32 s41, 0
	v_add_u32_e32 v146, 0, v3
	s_lshl_b32 s92, s12, 1
	v_lshlrev_b32_e32 v96, 1, v0
	s_mov_b64 s[12:13], s[18:19]
	s_mov_b64 s[10:11], s[16:17]
	s_barrier
	s_branch .LBB0_511

.LBB0_514:
	s_add_u32 s18, s16, 0xfff00080
	s_addc_u32 s19, s17, -1
	s_add_i32 s46, 0, 0x10000
	s_cmp_eq_u32 s52, 60
	s_cselect_b32 s21, s11, s19
	s_cselect_b32 s20, s10, s18
	v_add_u32_e32 v142, s46, v145
	s_cselect_b32 s19, s13, s49
	s_cselect_b32 s18, s12, s48
	s_add_i32 s50, 0, 0x14000
	ds_read_b128 v[148:151], v142
	ds_read_b128 v[152:155], v142 offset:1024
	ds_read_b128 v[156:159], v142 offset:2048
	ds_read_b128 v[160:163], v142 offset:3072
	v_add_u32_e32 v142, s50, v145
	ds_read_b128 v[164:167], v142
	ds_read_b128 v[168:171], v142 offset:1024
	ds_read_b128 v[172:175], v142 offset:2048
	ds_read_b128 v[176:179], v142 offset:3072
	s_add_i32 m0, s31, 0xc000
	ds_read_b128 v[180:183], v146
	ds_read_b128 v[184:187], v146 offset:1024
	ds_read_b128 v[188:191], v146 offset:2048
	ds_read_b128 v[204:207], v146 offset:3072
	ds_read_b128 v[208:211], v146 offset:4096
	ds_read_b128 v[212:215], v146 offset:5120
	ds_read_b128 v[216:219], v146 offset:6144
	ds_read_b128 v[220:223], v146 offset:7168
	global_load_lds_dwordx4 v138, s[16:17]
	s_add_i32 m0, s31, 0xe000
	s_nop 0
	global_load_lds_dwordx4 v140, s[16:17]
	s_waitcnt vmcnt(8) lgkmcnt(0)
	s_barrier
	s_setprio 1
	v_mfma_f32_16x16x32_bf16 v[126:129], v[148:151], v[180:183], v[126:129]
	v_mfma_f32_16x16x32_bf16 v[122:125], v[156:159], v[180:183], v[122:125]
	v_mfma_f32_16x16x32_bf16 v[118:121], v[148:151], v[188:191], v[118:121]
	v_mfma_f32_16x16x32_bf16 v[110:113], v[156:159], v[188:191], v[110:113]
	v_mfma_f32_16x16x32_bf16 v[102:105], v[148:151], v[208:211], v[102:105]
	v_mfma_f32_16x16x32_bf16 v[92:95], v[156:159], v[208:211], v[92:95]
	v_mfma_f32_16x16x32_bf16 v[84:87], v[148:151], v[216:219], v[84:87]
	v_mfma_f32_16x16x32_bf16 v[76:79], v[156:159], v[216:219], v[76:79]
	v_mfma_f32_16x16x32_bf16 v[126:129], v[152:155], v[184:187], v[126:129]
	v_mfma_f32_16x16x32_bf16 v[122:125], v[160:163], v[184:187], v[122:125]
	v_mfma_f32_16x16x32_bf16 v[118:121], v[152:155], v[204:207], v[118:121]
	v_mfma_f32_16x16x32_bf16 v[110:113], v[160:163], v[204:207], v[110:113]
	v_mfma_f32_16x16x32_bf16 v[102:105], v[152:155], v[212:215], v[102:105]
	v_mfma_f32_16x16x32_bf16 v[92:95], v[160:163], v[212:215], v[92:95]
	v_mfma_f32_16x16x32_bf16 v[84:87], v[152:155], v[220:223], v[84:87]
	v_mfma_f32_16x16x32_bf16 v[76:79], v[160:163], v[220:223], v[76:79]
	v_mfma_f32_16x16x32_bf16 v[114:117], v[164:167], v[180:183], v[114:117]
	v_mfma_f32_16x16x32_bf16 v[106:109], v[172:175], v[180:183], v[106:109]
	v_mfma_f32_16x16x32_bf16 v[98:101], v[164:167], v[188:191], v[98:101]
	v_mfma_f32_16x16x32_bf16 v[88:91], v[172:175], v[188:191], v[88:91]
	v_mfma_f32_16x16x32_bf16 v[80:83], v[164:167], v[208:211], v[80:83]
	v_mfma_f32_16x16x32_bf16 v[72:75], v[172:175], v[208:211], v[72:75]
	v_mfma_f32_16x16x32_bf16 v[68:71], v[164:167], v[216:219], v[68:71]
	v_mfma_f32_16x16x32_bf16 v[64:67], v[172:175], v[216:219], v[64:67]
	v_mfma_f32_16x16x32_bf16 v[114:117], v[168:171], v[184:187], v[114:117]
	v_mfma_f32_16x16x32_bf16 v[106:109], v[176:179], v[184:187], v[106:109]
	v_mfma_f32_16x16x32_bf16 v[98:101], v[168:171], v[204:207], v[98:101]
	v_mfma_f32_16x16x32_bf16 v[88:91], v[176:179], v[204:207], v[88:91]
	v_mfma_f32_16x16x32_bf16 v[80:83], v[168:171], v[212:215], v[80:83]
	v_mfma_f32_16x16x32_bf16 v[72:75], v[176:179], v[212:215], v[72:75]
	v_mfma_f32_16x16x32_bf16 v[68:71], v[168:171], v[220:223], v[68:71]
	v_mfma_f32_16x16x32_bf16 v[64:67], v[176:179], v[220:223], v[64:67]
	s_setprio 0
	s_barrier
	s_add_i32 s46, s46, s29
	v_lshl_add_u64 v[142:143], s[18:19], 0, v[134:135]
	s_mov_b32 m0, s46
	ds_read_b128 v[180:183], v146 offset:16384
	ds_read_b128 v[184:187], v146 offset:17408
	ds_read_b128 v[188:191], v146 offset:18432
	ds_read_b128 v[204:207], v146 offset:19456
	ds_read_b128 v[208:211], v146 offset:20480
	ds_read_b128 v[212:215], v146 offset:21504
	ds_read_b128 v[216:219], v146 offset:22528
	ds_read_b128 v[220:223], v146 offset:23552
	global_load_lds_dwordx4 v[142:143], off
	s_add_i32 m0, s46, 0x2000
	s_add_u32 s46, s18, 0x600000
	v_lshl_add_u64 v[192:193], s[18:19], 0, v[130:131]
	s_addc_u32 s47, s19, 0
	s_add_i32 s50, s50, s29
	global_load_lds_dwordx4 v[192:193], off
	s_mov_b32 m0, s50
	v_lshl_add_u64 v[198:199], s[20:21], 0, v[132:133]
	global_load_lds_dwordx4 v134, s[46:47]
	s_add_i32 m0, s50, 0x2000
	s_nop 0
	global_load_lds_dwordx4 v130, s[46:47]
	s_mov_b32 m0, s31
	v_lshl_add_u64 v[196:197], s[20:21], 0, v[136:137]
	global_load_lds_dwordx4 v[196:197], off
	s_mov_b32 m0, s36
	s_nop 0
	global_load_lds_dwordx4 v[198:199], off
	s_waitcnt vmcnt(8) lgkmcnt(0)
	s_barrier
	s_setprio 1
	v_mfma_f32_16x16x32_bf16 v[60:63], v[148:151], v[180:183], v[60:63]
	v_mfma_f32_16x16x32_bf16 v[56:59], v[156:159], v[180:183], v[56:59]
	v_mfma_f32_16x16x32_bf16 v[52:55], v[148:151], v[188:191], v[52:55]
	v_mfma_f32_16x16x32_bf16 v[44:47], v[156:159], v[188:191], v[44:47]
	v_mfma_f32_16x16x32_bf16 v[36:39], v[148:151], v[208:211], v[36:39]
	v_mfma_f32_16x16x32_bf16 v[28:31], v[156:159], v[208:211], v[28:31]
	v_mfma_f32_16x16x32_bf16 v[20:23], v[148:151], v[216:219], v[20:23]
	v_mfma_f32_16x16x32_bf16 v[12:15], v[156:159], v[216:219], v[12:15]
	v_mfma_f32_16x16x32_bf16 v[60:63], v[152:155], v[184:187], v[60:63]
	v_mfma_f32_16x16x32_bf16 v[56:59], v[160:163], v[184:187], v[56:59]
	v_mfma_f32_16x16x32_bf16 v[52:55], v[152:155], v[204:207], v[52:55]
	v_mfma_f32_16x16x32_bf16 v[44:47], v[160:163], v[204:207], v[44:47]
	v_mfma_f32_16x16x32_bf16 v[36:39], v[152:155], v[212:215], v[36:39]
	v_mfma_f32_16x16x32_bf16 v[28:31], v[160:163], v[212:215], v[28:31]
	v_mfma_f32_16x16x32_bf16 v[20:23], v[152:155], v[220:223], v[20:23]
	v_mfma_f32_16x16x32_bf16 v[12:15], v[160:163], v[220:223], v[12:15]
	v_mfma_f32_16x16x32_bf16 v[48:51], v[164:167], v[180:183], v[48:51]
	v_mfma_f32_16x16x32_bf16 v[40:43], v[172:175], v[180:183], v[40:43]
	v_mfma_f32_16x16x32_bf16 v[32:35], v[164:167], v[188:191], v[32:35]
	v_mfma_f32_16x16x32_bf16 v[24:27], v[172:175], v[188:191], v[24:27]
	v_mfma_f32_16x16x32_bf16 v[16:19], v[164:167], v[208:211], v[16:19]
	v_mfma_f32_16x16x32_bf16 v[8:11], v[172:175], v[208:211], v[8:11]
	v_mfma_f32_16x16x32_bf16 v[4:7], v[164:167], v[216:219], v[4:7]
	v_mfma_f32_16x16x32_bf16 v[0:3], v[172:175], v[216:219], v[0:3]
	v_mfma_f32_16x16x32_bf16 v[48:51], v[168:171], v[184:187], v[48:51]
	v_mfma_f32_16x16x32_bf16 v[40:43], v[176:179], v[184:187], v[40:43]
	v_mfma_f32_16x16x32_bf16 v[32:35], v[168:171], v[204:207], v[32:35]
	v_mfma_f32_16x16x32_bf16 v[24:27], v[176:179], v[204:207], v[24:27]
	v_mfma_f32_16x16x32_bf16 v[16:19], v[168:171], v[212:215], v[16:19]
	v_mfma_f32_16x16x32_bf16 v[8:11], v[176:179], v[212:215], v[8:11]
	v_mfma_f32_16x16x32_bf16 v[4:7], v[168:171], v[220:223], v[4:7]
	v_mfma_f32_16x16x32_bf16 v[0:3], v[176:179], v[220:223], v[0:3]
	s_setprio 0
	s_barrier
	s_add_i32 s46, 0, 0x18000
	v_add_u32_e32 v147, s46, v145
	s_add_i32 s47, 0, 0x1c000
	ds_read_b128 v[148:151], v147
	ds_read_b128 v[152:155], v147 offset:1024
	ds_read_b128 v[156:159], v147 offset:2048
	ds_read_b128 v[160:163], v147 offset:3072
	v_add_u32_e32 v147, s47, v145
	ds_read_b128 v[164:167], v147
	ds_read_b128 v[168:171], v147 offset:1024
	ds_read_b128 v[172:175], v147 offset:2048
	ds_read_b128 v[176:179], v147 offset:3072
	s_add_u32 s20, s20, 0x100000
	s_addc_u32 s21, s21, 0
	s_mov_b32 m0, s37
	ds_read_b128 v[180:183], v146 offset:32768
	ds_read_b128 v[184:187], v146 offset:33792
	ds_read_b128 v[188:191], v146 offset:34816
	ds_read_b128 v[204:207], v146 offset:35840
	ds_read_b128 v[208:211], v146 offset:36864
	ds_read_b128 v[212:215], v146 offset:37888
	ds_read_b128 v[216:219], v146 offset:38912
	ds_read_b128 v[220:223], v146 offset:39936
	global_load_lds_dwordx4 v136, s[20:21]
	s_mov_b32 m0, s38
	s_nop 0
	global_load_lds_dwordx4 v132, s[20:21]
	s_waitcnt vmcnt(8) lgkmcnt(0)
	s_barrier
	s_setprio 1
	v_mfma_f32_16x16x32_bf16 v[126:129], v[148:151], v[180:183], v[126:129]
	v_mfma_f32_16x16x32_bf16 v[122:125], v[156:159], v[180:183], v[122:125]
	v_mfma_f32_16x16x32_bf16 v[118:121], v[148:151], v[188:191], v[118:121]
	v_mfma_f32_16x16x32_bf16 v[110:113], v[156:159], v[188:191], v[110:113]
	v_mfma_f32_16x16x32_bf16 v[102:105], v[148:151], v[208:211], v[102:105]
	v_mfma_f32_16x16x32_bf16 v[92:95], v[156:159], v[208:211], v[92:95]
	v_mfma_f32_16x16x32_bf16 v[84:87], v[148:151], v[216:219], v[84:87]
	v_mfma_f32_16x16x32_bf16 v[76:79], v[156:159], v[216:219], v[76:79]
	v_mfma_f32_16x16x32_bf16 v[126:129], v[152:155], v[184:187], v[126:129]
	v_mfma_f32_16x16x32_bf16 v[122:125], v[160:163], v[184:187], v[122:125]
	v_mfma_f32_16x16x32_bf16 v[118:121], v[152:155], v[204:207], v[118:121]
	v_mfma_f32_16x16x32_bf16 v[110:113], v[160:163], v[204:207], v[110:113]
	v_mfma_f32_16x16x32_bf16 v[102:105], v[152:155], v[212:215], v[102:105]
	v_mfma_f32_16x16x32_bf16 v[92:95], v[160:163], v[212:215], v[92:95]
	v_mfma_f32_16x16x32_bf16 v[84:87], v[152:155], v[220:223], v[84:87]
	v_mfma_f32_16x16x32_bf16 v[76:79], v[160:163], v[220:223], v[76:79]
	v_mfma_f32_16x16x32_bf16 v[114:117], v[164:167], v[180:183], v[114:117]
	v_mfma_f32_16x16x32_bf16 v[106:109], v[172:175], v[180:183], v[106:109]
	v_mfma_f32_16x16x32_bf16 v[98:101], v[164:167], v[188:191], v[98:101]
	v_mfma_f32_16x16x32_bf16 v[88:91], v[172:175], v[188:191], v[88:91]
	v_mfma_f32_16x16x32_bf16 v[80:83], v[164:167], v[208:211], v[80:83]
	v_mfma_f32_16x16x32_bf16 v[72:75], v[172:175], v[208:211], v[72:75]
	v_mfma_f32_16x16x32_bf16 v[68:71], v[164:167], v[216:219], v[68:71]
	v_mfma_f32_16x16x32_bf16 v[64:67], v[172:175], v[216:219], v[64:67]
	v_mfma_f32_16x16x32_bf16 v[114:117], v[168:171], v[184:187], v[114:117]
	v_mfma_f32_16x16x32_bf16 v[106:109], v[176:179], v[184:187], v[106:109]
	v_mfma_f32_16x16x32_bf16 v[98:101], v[168:171], v[204:207], v[98:101]
	v_mfma_f32_16x16x32_bf16 v[88:91], v[176:179], v[204:207], v[88:91]
	v_mfma_f32_16x16x32_bf16 v[80:83], v[168:171], v[212:215], v[80:83]
	v_mfma_f32_16x16x32_bf16 v[72:75], v[176:179], v[212:215], v[72:75]
	v_mfma_f32_16x16x32_bf16 v[68:71], v[168:171], v[220:223], v[68:71]
	v_mfma_f32_16x16x32_bf16 v[64:67], v[176:179], v[220:223], v[64:67]
	s_setprio 0
	s_barrier
	s_add_i32 s20, s46, s29
	v_lshl_add_u64 v[142:143], v[142:143], 0, s[82:83]
	s_mov_b32 m0, s20
	ds_read_b128 v[180:183], v146 offset:49152
	ds_read_b128 v[184:187], v146 offset:50176
	ds_read_b128 v[188:191], v146 offset:51200
	ds_read_b128 v[204:207], v146 offset:52224
	ds_read_b128 v[208:211], v146 offset:53248
	ds_read_b128 v[212:215], v146 offset:54272
	ds_read_b128 v[216:219], v146 offset:55296
	ds_read_b128 v[220:223], v146 offset:56320
	global_load_lds_dwordx4 v[142:143], off
	s_add_i32 m0, s20, 0x2000
	s_add_u32 s18, s18, 0x600080
	v_lshl_add_u64 v[142:143], v[192:193], 0, s[82:83]
	s_addc_u32 s19, s19, 0
	s_add_i32 s20, s47, s29
	global_load_lds_dwordx4 v[142:143], off
	s_mov_b32 m0, s20
	s_nop 0
	global_load_lds_dwordx4 v134, s[18:19]
	s_add_i32 m0, s20, 0x2000
	s_nop 0
	global_load_lds_dwordx4 v130, s[18:19]
	s_mov_b32 m0, s39
	v_lshl_add_u64 v[142:143], v[196:197], 0, s[82:83]
	global_load_lds_dwordx4 v[142:143], off
	s_mov_b32 m0, s40
	v_lshl_add_u64 v[142:143], v[198:199], 0, s[82:83]
	global_load_lds_dwordx4 v[142:143], off
	s_waitcnt vmcnt(8) lgkmcnt(0)
	s_barrier
	s_setprio 1
	v_mfma_f32_16x16x32_bf16 v[60:63], v[148:151], v[180:183], v[60:63]
	v_mfma_f32_16x16x32_bf16 v[56:59], v[156:159], v[180:183], v[56:59]
	v_mfma_f32_16x16x32_bf16 v[52:55], v[148:151], v[188:191], v[52:55]
	v_mfma_f32_16x16x32_bf16 v[44:47], v[156:159], v[188:191], v[44:47]
	v_mfma_f32_16x16x32_bf16 v[36:39], v[148:151], v[208:211], v[36:39]
	v_mfma_f32_16x16x32_bf16 v[28:31], v[156:159], v[208:211], v[28:31]
	v_mfma_f32_16x16x32_bf16 v[20:23], v[148:151], v[216:219], v[20:23]
	v_mfma_f32_16x16x32_bf16 v[12:15], v[156:159], v[216:219], v[12:15]
	v_mfma_f32_16x16x32_bf16 v[60:63], v[152:155], v[184:187], v[60:63]
	v_mfma_f32_16x16x32_bf16 v[56:59], v[160:163], v[184:187], v[56:59]
	v_mfma_f32_16x16x32_bf16 v[52:55], v[152:155], v[204:207], v[52:55]
	v_mfma_f32_16x16x32_bf16 v[44:47], v[160:163], v[204:207], v[44:47]
	v_mfma_f32_16x16x32_bf16 v[36:39], v[152:155], v[212:215], v[36:39]
	v_mfma_f32_16x16x32_bf16 v[28:31], v[160:163], v[212:215], v[28:31]
	v_mfma_f32_16x16x32_bf16 v[20:23], v[152:155], v[220:223], v[20:23]
	v_mfma_f32_16x16x32_bf16 v[12:15], v[160:163], v[220:223], v[12:15]
	v_mfma_f32_16x16x32_bf16 v[48:51], v[164:167], v[180:183], v[48:51]
	v_mfma_f32_16x16x32_bf16 v[40:43], v[172:175], v[180:183], v[40:43]
	v_mfma_f32_16x16x32_bf16 v[32:35], v[164:167], v[188:191], v[32:35]
	v_mfma_f32_16x16x32_bf16 v[24:27], v[172:175], v[188:191], v[24:27]
	v_mfma_f32_16x16x32_bf16 v[16:19], v[164:167], v[208:211], v[16:19]
	v_mfma_f32_16x16x32_bf16 v[8:11], v[172:175], v[208:211], v[8:11]
	v_mfma_f32_16x16x32_bf16 v[4:7], v[164:167], v[216:219], v[4:7]
	v_mfma_f32_16x16x32_bf16 v[0:3], v[172:175], v[216:219], v[0:3]
	v_mfma_f32_16x16x32_bf16 v[48:51], v[168:171], v[184:187], v[48:51]
	v_mfma_f32_16x16x32_bf16 v[40:43], v[176:179], v[184:187], v[40:43]
	v_mfma_f32_16x16x32_bf16 v[32:35], v[168:171], v[204:207], v[32:35]
	v_mfma_f32_16x16x32_bf16 v[24:27], v[176:179], v[204:207], v[24:27]
	v_mfma_f32_16x16x32_bf16 v[16:19], v[168:171], v[212:215], v[16:19]
	v_mfma_f32_16x16x32_bf16 v[8:11], v[176:179], v[212:215], v[8:11]
	v_mfma_f32_16x16x32_bf16 v[4:7], v[168:171], v[220:223], v[4:7]
	v_mfma_f32_16x16x32_bf16 v[0:3], v[176:179], v[220:223], v[0:3]
	s_setprio 0
	s_barrier
	s_add_i32 s52, s52, 2
	s_add_u32 s16, s16, 0x100
	s_addc_u32 s17, s17, 0
	s_add_u32 s48, s48, 0x100
	s_addc_u32 s49, s49, 0
	s_cmp_gt_u32 s52, 61
	s_cbranch_scc0 .LBB0_514
	s_and_b64 vcc, exec, s[8:9]
	s_cbranch_vccz .LBB0_517
	s_barrier

.LBB0_573:
	s_and_b32 s48, s0, 7
	s_add_u32 s10, s4, 0x48f00000
	v_lshrrev_b32_e32 v12, 1, v10
	s_addc_u32 s11, s5, 0
	v_and_b32_e32 v12, 24, v12
	s_lshl_b32 s13, s13, 5
	v_and_b32_e32 v11, 15, v10
	v_lshlrev_b32_e32 v13, 1, v12
	v_lshlrev_b32_e32 v10, 2, v10
	s_and_b32 s16, s13, 0x60
	s_add_i32 m0, s19, 0x18000
	v_lshl_add_u64 v[0:1], v[0:1], 0, s[82:83]
	v_lshl_or_b32 v144, s14, 6, v11
	v_lshl_or_b32 v11, v11, 6, v13
	s_lshl_b32 s14, s14, 13
	v_and_b32_e32 v10, 32, v10
	s_lshl_b32 s13, s16, 7
	s_waitcnt vmcnt(2)
	s_barrier
	global_load_lds_dwordx4 v[0:1], off
	s_add_i32 m0, s19, 0x1a000
	v_bitop3_b32 v13, v11, s14, v10 bitop3:0xde
	s_add_u32 s14, s4, 0x700080
	v_mov_b32_e32 v137, v97
	v_lshl_add_u64 v[0:1], v[2:3], 0, s[82:83]
	s_addc_u32 s15, s5, 0
	s_add_i32 s42, s19, 0x8000
	v_mov_b32_e32 v133, v97
	global_load_lds_dwordx4 v[0:1], off
	s_mov_b32 m0, s42
	s_add_i32 s43, s19, 0xa000
	global_load_lds_dwordx4 v136, s[14:15]
	v_lshl_add_u64 v[0:1], s[14:15], 0, v[132:133]
	s_add_u32 s14, s20, 0x600080
	s_mov_b32 m0, s43
	s_addc_u32 s15, s21, 0
	global_load_lds_dwordx4 v[0:1], off
	s_add_i32 m0, s19, 0x1c000
	s_nop 0
	global_load_lds_dwordx4 v134, s[14:15]
	s_add_i32 m0, s19, 0x1e000
	s_cmpk_lt_u32 s12, 0x100
	global_load_lds_dwordx4 v130, s[14:15]
	v_lshlrev_b32_e32 v0, 13, v8
	v_and_b32_e32 v0, 0xffffc000, v0
	v_lshl_add_u32 v0, v7, 10, v0
	v_and_b32_e32 v1, 1, v8
	v_lshl_or_b32 v0, v1, 6, v0
	v_lshl_add_u32 v96, v9, 1, v0
	v_lshlrev_b32_e32 v0, 13, v4
	v_and_b32_e32 v0, 0xffffc000, v0
	v_bitop3_b32 v145, v11, s13, v10 bitop3:0xde
	s_cselect_b64 s[12:13], -1, 0
	s_add_u32 s4, s4, 0x720080
	v_lshl_add_u32 v0, v5, 10, v0
	v_and_b32_e32 v1, 1, v4
	s_waitcnt vmcnt(6)
	s_addc_u32 s5, s5, 0
	v_lshl_or_b32 v0, v1, 6, v0
	v_lshl_add_u64 v[138:139], s[4:5], 0, v[96:97]
	v_lshl_add_u32 v96, v6, 1, v0
	v_lshl_add_u64 v[140:141], s[4:5], 0, v[96:97]
	s_mov_b32 s44, 0
	v_add_u32_e32 v146, 0, v13
	s_lshl_b32 s92, s16, 1
	v_lshlrev_b32_e32 v96, 1, v12
	s_mov_b64 s[16:17], s[20:21]
	s_barrier
	s_branch .LBB0_576

.LBB0_579:
	s_add_u32 s22, s20, 0x100
	s_addc_u32 s23, s21, 0
	s_add_u32 s36, s15, s20
	s_addc_u32 s37, s49, s21
	s_cmp_eq_u32 s52, 4
	s_cselect_b32 s38, 0, s22
	s_cselect_b32 s39, 0, s23
	s_cselect_b32 s36, s16, s36
	s_cselect_b32 s37, s17, s37
	s_add_u32 s38, s6, s38
	s_addc_u32 s39, s7, s39
	s_add_i32 s46, 0, 0x10000
	v_add_u32_e32 v142, s46, v145
	s_add_i32 s47, 0, 0x14000
	ds_read_b128 v[148:151], v142
	ds_read_b128 v[152:155], v142 offset:1024
	ds_read_b128 v[156:159], v142 offset:2048
	ds_read_b128 v[160:163], v142 offset:3072
	v_add_u32_e32 v142, s47, v145
	ds_read_b128 v[164:167], v142
	ds_read_b128 v[168:171], v142 offset:1024
	ds_read_b128 v[172:175], v142 offset:2048
	ds_read_b128 v[176:179], v142 offset:3072
	v_lshl_add_u64 v[142:143], v[138:139], 0, s[20:21]
	s_add_i32 m0, s19, 0xc000
	ds_read_b128 v[180:183], v146
	ds_read_b128 v[184:187], v146 offset:1024
	ds_read_b128 v[188:191], v146 offset:2048
	ds_read_b128 v[196:199], v146 offset:3072
	ds_read_b128 v[200:203], v146 offset:4096
	ds_read_b128 v[204:207], v146 offset:5120
	ds_read_b128 v[208:211], v146 offset:6144
	ds_read_b128 v[212:215], v146 offset:7168
	global_load_lds_dwordx4 v[142:143], off
	s_add_i32 m0, s19, 0xe000
	v_lshl_add_u64 v[142:143], v[140:141], 0, s[20:21]
	global_load_lds_dwordx4 v[142:143], off
	s_waitcnt vmcnt(8) lgkmcnt(0)
	s_barrier
	s_setprio 1
	v_mfma_f32_16x16x32_bf16 v[126:129], v[148:151], v[180:183], v[126:129]
	v_mfma_f32_16x16x32_bf16 v[122:125], v[156:159], v[180:183], v[122:125]
	v_mfma_f32_16x16x32_bf16 v[118:121], v[148:151], v[188:191], v[118:121]
	v_mfma_f32_16x16x32_bf16 v[110:113], v[156:159], v[188:191], v[110:113]
	v_mfma_f32_16x16x32_bf16 v[102:105], v[148:151], v[200:203], v[102:105]
	v_mfma_f32_16x16x32_bf16 v[92:95], v[156:159], v[200:203], v[92:95]
	v_mfma_f32_16x16x32_bf16 v[84:87], v[148:151], v[208:211], v[84:87]
	v_mfma_f32_16x16x32_bf16 v[76:79], v[156:159], v[208:211], v[76:79]
	v_mfma_f32_16x16x32_bf16 v[126:129], v[152:155], v[184:187], v[126:129]
	v_mfma_f32_16x16x32_bf16 v[122:125], v[160:163], v[184:187], v[122:125]
	v_mfma_f32_16x16x32_bf16 v[118:121], v[152:155], v[196:199], v[118:121]
	v_mfma_f32_16x16x32_bf16 v[110:113], v[160:163], v[196:199], v[110:113]
	v_mfma_f32_16x16x32_bf16 v[102:105], v[152:155], v[204:207], v[102:105]
	v_mfma_f32_16x16x32_bf16 v[92:95], v[160:163], v[204:207], v[92:95]
	v_mfma_f32_16x16x32_bf16 v[84:87], v[152:155], v[212:215], v[84:87]
	v_mfma_f32_16x16x32_bf16 v[76:79], v[160:163], v[212:215], v[76:79]
	v_mfma_f32_16x16x32_bf16 v[114:117], v[164:167], v[180:183], v[114:117]
	v_mfma_f32_16x16x32_bf16 v[106:109], v[172:175], v[180:183], v[106:109]
	v_mfma_f32_16x16x32_bf16 v[98:101], v[164:167], v[188:191], v[98:101]
	v_mfma_f32_16x16x32_bf16 v[88:91], v[172:175], v[188:191], v[88:91]
	v_mfma_f32_16x16x32_bf16 v[80:83], v[164:167], v[200:203], v[80:83]
	v_mfma_f32_16x16x32_bf16 v[72:75], v[172:175], v[200:203], v[72:75]
	v_mfma_f32_16x16x32_bf16 v[68:71], v[164:167], v[208:211], v[68:71]
	v_mfma_f32_16x16x32_bf16 v[64:67], v[172:175], v[208:211], v[64:67]
	v_mfma_f32_16x16x32_bf16 v[114:117], v[168:171], v[184:187], v[114:117]
	v_mfma_f32_16x16x32_bf16 v[106:109], v[176:179], v[184:187], v[106:109]
	v_mfma_f32_16x16x32_bf16 v[98:101], v[168:171], v[196:199], v[98:101]
	v_mfma_f32_16x16x32_bf16 v[88:91], v[176:179], v[196:199], v[88:91]
	v_mfma_f32_16x16x32_bf16 v[80:83], v[168:171], v[204:207], v[80:83]
	v_mfma_f32_16x16x32_bf16 v[72:75], v[176:179], v[204:207], v[72:75]
	v_mfma_f32_16x16x32_bf16 v[68:71], v[168:171], v[212:215], v[68:71]
	v_mfma_f32_16x16x32_bf16 v[64:67], v[176:179], v[212:215], v[64:67]
	s_setprio 0
	s_barrier
	s_add_i32 s20, s46, s29
	v_lshl_add_u64 v[142:143], s[36:37], 0, v[134:135]
	s_mov_b32 m0, s20
	ds_read_b128 v[180:183], v146 offset:16384
	ds_read_b128 v[184:187], v146 offset:17408
	ds_read_b128 v[188:191], v146 offset:18432
	ds_read_b128 v[196:199], v146 offset:19456
	ds_read_b128 v[200:203], v146 offset:20480
	ds_read_b128 v[204:207], v146 offset:21504
	ds_read_b128 v[208:211], v146 offset:22528
	ds_read_b128 v[212:215], v146 offset:23552
	global_load_lds_dwordx4 v[142:143], off
	s_add_i32 m0, s20, 0x2000
	s_add_u32 s20, s36, 0x600000
	v_lshl_add_u64 v[192:193], s[36:37], 0, v[130:131]
	s_addc_u32 s21, s37, 0
	s_add_i32 s46, s47, s29
	global_load_lds_dwordx4 v[192:193], off
	s_mov_b32 m0, s46
	v_lshl_add_u64 v[218:219], s[38:39], 0, v[132:133]
	global_load_lds_dwordx4 v134, s[20:21]
	s_add_i32 m0, s46, 0x2000
	s_nop 0
	global_load_lds_dwordx4 v130, s[20:21]
	s_mov_b32 m0, s19
	v_lshl_add_u64 v[216:217], s[38:39], 0, v[136:137]
	global_load_lds_dwordx4 v[216:217], off
	s_mov_b32 m0, s31
	s_nop 0
	global_load_lds_dwordx4 v[218:219], off
	s_waitcnt vmcnt(8) lgkmcnt(0)
	s_barrier
	s_setprio 1
	v_mfma_f32_16x16x32_bf16 v[60:63], v[148:151], v[180:183], v[60:63]
	v_mfma_f32_16x16x32_bf16 v[56:59], v[156:159], v[180:183], v[56:59]
	v_mfma_f32_16x16x32_bf16 v[52:55], v[148:151], v[188:191], v[52:55]
	v_mfma_f32_16x16x32_bf16 v[44:47], v[156:159], v[188:191], v[44:47]
	v_mfma_f32_16x16x32_bf16 v[36:39], v[148:151], v[200:203], v[36:39]
	v_mfma_f32_16x16x32_bf16 v[28:31], v[156:159], v[200:203], v[28:31]
	v_mfma_f32_16x16x32_bf16 v[20:23], v[148:151], v[208:211], v[20:23]
	v_mfma_f32_16x16x32_bf16 v[12:15], v[156:159], v[208:211], v[12:15]
	v_mfma_f32_16x16x32_bf16 v[60:63], v[152:155], v[184:187], v[60:63]
	v_mfma_f32_16x16x32_bf16 v[56:59], v[160:163], v[184:187], v[56:59]
	v_mfma_f32_16x16x32_bf16 v[52:55], v[152:155], v[196:199], v[52:55]
	v_mfma_f32_16x16x32_bf16 v[44:47], v[160:163], v[196:199], v[44:47]
	v_mfma_f32_16x16x32_bf16 v[36:39], v[152:155], v[204:207], v[36:39]
	v_mfma_f32_16x16x32_bf16 v[28:31], v[160:163], v[204:207], v[28:31]
	v_mfma_f32_16x16x32_bf16 v[20:23], v[152:155], v[212:215], v[20:23]
	v_mfma_f32_16x16x32_bf16 v[12:15], v[160:163], v[212:215], v[12:15]
	v_mfma_f32_16x16x32_bf16 v[48:51], v[164:167], v[180:183], v[48:51]
	v_mfma_f32_16x16x32_bf16 v[40:43], v[172:175], v[180:183], v[40:43]
	v_mfma_f32_16x16x32_bf16 v[32:35], v[164:167], v[188:191], v[32:35]
	v_mfma_f32_16x16x32_bf16 v[24:27], v[172:175], v[188:191], v[24:27]
	v_mfma_f32_16x16x32_bf16 v[16:19], v[164:167], v[200:203], v[16:19]
	v_mfma_f32_16x16x32_bf16 v[8:11], v[172:175], v[200:203], v[8:11]
	v_mfma_f32_16x16x32_bf16 v[4:7], v[164:167], v[208:211], v[4:7]
	v_mfma_f32_16x16x32_bf16 v[0:3], v[172:175], v[208:211], v[0:3]
	v_mfma_f32_16x16x32_bf16 v[48:51], v[168:171], v[184:187], v[48:51]
	v_mfma_f32_16x16x32_bf16 v[40:43], v[176:179], v[184:187], v[40:43]
	v_mfma_f32_16x16x32_bf16 v[32:35], v[168:171], v[196:199], v[32:35]
	v_mfma_f32_16x16x32_bf16 v[24:27], v[176:179], v[196:199], v[24:27]
	v_mfma_f32_16x16x32_bf16 v[16:19], v[168:171], v[204:207], v[16:19]
	v_mfma_f32_16x16x32_bf16 v[8:11], v[176:179], v[204:207], v[8:11]
	v_mfma_f32_16x16x32_bf16 v[4:7], v[168:171], v[212:215], v[4:7]
	v_mfma_f32_16x16x32_bf16 v[0:3], v[176:179], v[212:215], v[0:3]
	s_setprio 0
	s_barrier
	s_add_i32 s46, 0, 0x18000
	v_add_u32_e32 v147, s46, v145
	s_add_i32 s47, 0, 0x1c000
	ds_read_b128 v[148:151], v147
	ds_read_b128 v[152:155], v147 offset:1024
	ds_read_b128 v[156:159], v147 offset:2048
	ds_read_b128 v[160:163], v147 offset:3072
	v_add_u32_e32 v147, s47, v145
	ds_read_b128 v[164:167], v147
	ds_read_b128 v[168:171], v147 offset:1024
	ds_read_b128 v[172:175], v147 offset:2048
	ds_read_b128 v[176:179], v147 offset:3072
	s_add_u32 s20, s38, 0x20000
	s_addc_u32 s21, s39, 0
	s_mov_b32 m0, s40
	ds_read_b128 v[180:183], v146 offset:32768
	ds_read_b128 v[184:187], v146 offset:33792
	ds_read_b128 v[188:191], v146 offset:34816
	ds_read_b128 v[196:199], v146 offset:35840
	ds_read_b128 v[200:203], v146 offset:36864
	ds_read_b128 v[204:207], v146 offset:37888
	ds_read_b128 v[208:211], v146 offset:38912
	ds_read_b128 v[212:215], v146 offset:39936
	global_load_lds_dwordx4 v136, s[20:21]
	s_mov_b32 m0, s41
	s_nop 0
	global_load_lds_dwordx4 v132, s[20:21]
	s_waitcnt vmcnt(8) lgkmcnt(0)
	s_barrier
	s_setprio 1
	v_mfma_f32_16x16x32_bf16 v[126:129], v[148:151], v[180:183], v[126:129]
	v_mfma_f32_16x16x32_bf16 v[122:125], v[156:159], v[180:183], v[122:125]
	v_mfma_f32_16x16x32_bf16 v[118:121], v[148:151], v[188:191], v[118:121]
	v_mfma_f32_16x16x32_bf16 v[110:113], v[156:159], v[188:191], v[110:113]
	v_mfma_f32_16x16x32_bf16 v[102:105], v[148:151], v[200:203], v[102:105]
	v_mfma_f32_16x16x32_bf16 v[92:95], v[156:159], v[200:203], v[92:95]
	v_mfma_f32_16x16x32_bf16 v[84:87], v[148:151], v[208:211], v[84:87]
	v_mfma_f32_16x16x32_bf16 v[76:79], v[156:159], v[208:211], v[76:79]
	v_mfma_f32_16x16x32_bf16 v[126:129], v[152:155], v[184:187], v[126:129]
	v_mfma_f32_16x16x32_bf16 v[122:125], v[160:163], v[184:187], v[122:125]
	v_mfma_f32_16x16x32_bf16 v[118:121], v[152:155], v[196:199], v[118:121]
	v_mfma_f32_16x16x32_bf16 v[110:113], v[160:163], v[196:199], v[110:113]
	v_mfma_f32_16x16x32_bf16 v[102:105], v[152:155], v[204:207], v[102:105]
	v_mfma_f32_16x16x32_bf16 v[92:95], v[160:163], v[204:207], v[92:95]
	v_mfma_f32_16x16x32_bf16 v[84:87], v[152:155], v[212:215], v[84:87]
	v_mfma_f32_16x16x32_bf16 v[76:79], v[160:163], v[212:215], v[76:79]
	v_mfma_f32_16x16x32_bf16 v[114:117], v[164:167], v[180:183], v[114:117]
	v_mfma_f32_16x16x32_bf16 v[106:109], v[172:175], v[180:183], v[106:109]
	v_mfma_f32_16x16x32_bf16 v[98:101], v[164:167], v[188:191], v[98:101]
	v_mfma_f32_16x16x32_bf16 v[88:91], v[172:175], v[188:191], v[88:91]
	v_mfma_f32_16x16x32_bf16 v[80:83], v[164:167], v[200:203], v[80:83]
	v_mfma_f32_16x16x32_bf16 v[72:75], v[172:175], v[200:203], v[72:75]
	v_mfma_f32_16x16x32_bf16 v[68:71], v[164:167], v[208:211], v[68:71]
	v_mfma_f32_16x16x32_bf16 v[64:67], v[172:175], v[208:211], v[64:67]
	v_mfma_f32_16x16x32_bf16 v[114:117], v[168:171], v[184:187], v[114:117]
	v_mfma_f32_16x16x32_bf16 v[106:109], v[176:179], v[184:187], v[106:109]
	v_mfma_f32_16x16x32_bf16 v[98:101], v[168:171], v[196:199], v[98:101]
	v_mfma_f32_16x16x32_bf16 v[88:91], v[176:179], v[196:199], v[88:91]
	v_mfma_f32_16x16x32_bf16 v[80:83], v[168:171], v[204:207], v[80:83]
	v_mfma_f32_16x16x32_bf16 v[72:75], v[176:179], v[204:207], v[72:75]
	v_mfma_f32_16x16x32_bf16 v[68:71], v[168:171], v[212:215], v[68:71]
	v_mfma_f32_16x16x32_bf16 v[64:67], v[176:179], v[212:215], v[64:67]
	s_setprio 0
	s_barrier
	s_add_i32 s20, s46, s29
	v_lshl_add_u64 v[142:143], v[142:143], 0, s[82:83]
	s_mov_b32 m0, s20
	ds_read_b128 v[180:183], v146 offset:49152
	ds_read_b128 v[184:187], v146 offset:50176
	ds_read_b128 v[188:191], v146 offset:51200
	ds_read_b128 v[196:199], v146 offset:52224
	ds_read_b128 v[200:203], v146 offset:53248
	ds_read_b128 v[204:207], v146 offset:54272
	ds_read_b128 v[208:211], v146 offset:55296
	ds_read_b128 v[212:215], v146 offset:56320
	global_load_lds_dwordx4 v[142:143], off
	s_add_i32 m0, s20, 0x2000
	s_add_u32 s20, s36, 0x600080
	v_lshl_add_u64 v[142:143], v[192:193], 0, s[82:83]
	s_addc_u32 s21, s37, 0
	s_add_i32 s36, s47, s29
	global_load_lds_dwordx4 v[142:143], off
	s_mov_b32 m0, s36
	s_nop 0
	global_load_lds_dwordx4 v134, s[20:21]
	s_add_i32 m0, s36, 0x2000
	s_nop 0
	global_load_lds_dwordx4 v130, s[20:21]
	s_mov_b32 m0, s42
	v_lshl_add_u64 v[142:143], v[216:217], 0, s[82:83]
	global_load_lds_dwordx4 v[142:143], off
	s_mov_b32 m0, s43
	v_lshl_add_u64 v[142:143], v[218:219], 0, s[82:83]
	global_load_lds_dwordx4 v[142:143], off
	s_waitcnt vmcnt(8) lgkmcnt(0)
	s_barrier
	s_setprio 1
	v_mfma_f32_16x16x32_bf16 v[60:63], v[148:151], v[180:183], v[60:63]
	v_mfma_f32_16x16x32_bf16 v[56:59], v[156:159], v[180:183], v[56:59]
	v_mfma_f32_16x16x32_bf16 v[52:55], v[148:151], v[188:191], v[52:55]
	v_mfma_f32_16x16x32_bf16 v[44:47], v[156:159], v[188:191], v[44:47]
	v_mfma_f32_16x16x32_bf16 v[36:39], v[148:151], v[200:203], v[36:39]
	v_mfma_f32_16x16x32_bf16 v[28:31], v[156:159], v[200:203], v[28:31]
	v_mfma_f32_16x16x32_bf16 v[20:23], v[148:151], v[208:211], v[20:23]
	v_mfma_f32_16x16x32_bf16 v[12:15], v[156:159], v[208:211], v[12:15]
	v_mfma_f32_16x16x32_bf16 v[60:63], v[152:155], v[184:187], v[60:63]
	v_mfma_f32_16x16x32_bf16 v[56:59], v[160:163], v[184:187], v[56:59]
	v_mfma_f32_16x16x32_bf16 v[52:55], v[152:155], v[196:199], v[52:55]
	v_mfma_f32_16x16x32_bf16 v[44:47], v[160:163], v[196:199], v[44:47]
	v_mfma_f32_16x16x32_bf16 v[36:39], v[152:155], v[204:207], v[36:39]
	v_mfma_f32_16x16x32_bf16 v[28:31], v[160:163], v[204:207], v[28:31]
	v_mfma_f32_16x16x32_bf16 v[20:23], v[152:155], v[212:215], v[20:23]
	v_mfma_f32_16x16x32_bf16 v[12:15], v[160:163], v[212:215], v[12:15]
	v_mfma_f32_16x16x32_bf16 v[48:51], v[164:167], v[180:183], v[48:51]
	v_mfma_f32_16x16x32_bf16 v[40:43], v[172:175], v[180:183], v[40:43]
	v_mfma_f32_16x16x32_bf16 v[32:35], v[164:167], v[188:191], v[32:35]
	v_mfma_f32_16x16x32_bf16 v[24:27], v[172:175], v[188:191], v[24:27]
	v_mfma_f32_16x16x32_bf16 v[16:19], v[164:167], v[200:203], v[16:19]
	v_mfma_f32_16x16x32_bf16 v[8:11], v[172:175], v[200:203], v[8:11]
	v_mfma_f32_16x16x32_bf16 v[4:7], v[164:167], v[208:211], v[4:7]
	v_mfma_f32_16x16x32_bf16 v[0:3], v[172:175], v[208:211], v[0:3]
	v_mfma_f32_16x16x32_bf16 v[48:51], v[168:171], v[184:187], v[48:51]
	v_mfma_f32_16x16x32_bf16 v[40:43], v[176:179], v[184:187], v[40:43]
	v_mfma_f32_16x16x32_bf16 v[32:35], v[168:171], v[196:199], v[32:35]
	v_mfma_f32_16x16x32_bf16 v[24:27], v[176:179], v[196:199], v[24:27]
	v_mfma_f32_16x16x32_bf16 v[16:19], v[168:171], v[204:207], v[16:19]
	v_mfma_f32_16x16x32_bf16 v[8:11], v[176:179], v[204:207], v[8:11]
	v_mfma_f32_16x16x32_bf16 v[4:7], v[168:171], v[212:215], v[4:7]
	v_mfma_f32_16x16x32_bf16 v[0:3], v[176:179], v[212:215], v[0:3]
	s_setprio 0
	s_barrier
	s_add_i32 s52, s52, 2
	s_cmp_gt_u32 s52, 5
	s_mov_b64 s[20:21], s[22:23]
	s_cbranch_scc0 .LBB0_579
	s_and_b64 vcc, exec, s[12:13]
	s_cbranch_vccz .LBB0_582
	s_barrier

.LBB0_722:
	s_add_u32 s41, s6, 0x18b00000
	s_addc_u32 s42, s7, 0
	s_add_u32 s43, s6, 0x24f00000
	s_addc_u32 s44, s7, 0
	s_lshl_b32 s4, s12, 5
	s_and_b32 s14, s4, 0x60
	s_add_i32 m0, s29, 0x18000
	v_lshl_add_u64 v[6:7], v[6:7], 0, s[82:83]
	s_lshl_b32 s13, s11, 13
	s_lshl_b32 s12, s14, 7
	s_waitcnt vmcnt(2)
	s_barrier
	global_load_lds_dwordx4 v[6:7], off
	v_lshl_add_u64 v[4:5], v[4:5], 0, s[82:83]
	s_add_i32 m0, s29, 0x1a000
	s_add_i32 s45, s29, 0x8000
	s_add_i32 s48, s29, 0xa000
	global_load_lds_dwordx4 v[4:5], off
	v_lshl_add_u64 v[0:1], v[0:1], 0, s[82:83]
	s_mov_b32 m0, s45
	s_add_u32 s4, s36, 0x80080
	global_load_lds_dwordx4 v[0:1], off
	v_lshl_add_u64 v[0:1], v[2:3], 0, s[82:83]
	s_mov_b32 m0, s48
	s_addc_u32 s5, s37, 0
	global_load_lds_dwordx4 v[0:1], off
	s_add_i32 m0, s29, 0x1c000
	s_nop 0
	global_load_lds_dwordx4 v96, s[4:5]
	s_add_i32 m0, s29, 0x1e000
	s_cmpk_lt_u32 s10, 0x100
	global_load_lds_dwordx4 v208, s[4:5]
	v_lshrrev_b32_e32 v1, 1, v8
	v_and_b32_e32 v1, 24, v1
	v_and_b32_e32 v0, 15, v8
	v_lshlrev_b32_e32 v2, 1, v1
	v_lshl_or_b32 v233, s11, 6, v0
	v_lshl_or_b32 v0, v0, 6, v2
	v_lshlrev_b32_e32 v2, 2, v8
	v_and_b32_e32 v2, 32, v2
	v_bitop3_b32 v3, v0, s13, v2 bitop3:0xde
	v_bitop3_b32 v234, v0, s12, v2 bitop3:0xde
	v_lshlrev_b32_e32 v0, 15, v9
	v_and_b32_e32 v0, 0xffff0000, v0
	v_or_b32_e32 v235, s14, v1
	v_lshl_add_u32 v0, v10, 12, v0
	v_and_b32_e32 v1, 1, v9
	v_lshl_or_b32 v0, v1, 6, v0
	v_lshl_add_u32 v210, v11, 1, v0
	v_lshlrev_b32_e32 v0, 15, v12
	v_and_b32_e32 v0, 0xffff0000, v0
	s_waitcnt vmcnt(6)
	v_lshl_add_u32 v0, v13, 12, v0
	v_and_b32_e32 v1, 1, v12
	v_lshl_or_b32 v0, v1, 6, v0
	s_cselect_b64 s[10:11], -1, 0
	s_bfe_i64 s[12:13], s[92:93], 0x200000
	v_mov_b32_e32 v211, v97
	v_lshl_add_u32 v212, v14, 1, v0
	v_mov_b32_e32 v213, v97
	s_mov_b32 s49, 0
	v_add_u32_e32 v236, 0, v3
	s_mov_b64 s[16:17], s[22:23]
	s_mov_b64 s[18:19], s[36:37]
	s_barrier
	s_branch .LBB0_725

.LBB0_736:
	s_add_i32 s46, s38, 2
	s_add_u32 s36, s22, 0xfff80080
	s_addc_u32 s37, s23, -1
	s_add_i32 s47, 0, 0x10000
	s_cmp_eq_u32 s21, s38
	s_cselect_b32 s39, s17, s37
	s_cselect_b32 s38, s16, s36
	s_cselect_b32 s37, s19, s58
	s_cselect_b32 s36, s18, s57
	s_add_i32 s50, 0, 0x14000
	v_add_u32_e32 v142, s47, v234
	v_add_u32_e32 v158, s50, v234
	ds_read_b128 v[130:133], v142
	ds_read_b128 v[134:137], v142 offset:1024
	ds_read_b128 v[138:141], v142 offset:2048
	ds_read_b128 v[142:145], v142 offset:3072
	ds_read_b128 v[146:149], v158
	ds_read_b128 v[150:153], v158 offset:1024
	ds_read_b128 v[154:157], v158 offset:2048
	ds_read_b128 v[158:161], v158 offset:3072
	s_add_i32 m0, s29, 0xc000
	ds_read_b128 v[162:165], v236
	ds_read_b128 v[166:169], v236 offset:1024
	ds_read_b128 v[170:173], v236 offset:2048
	ds_read_b128 v[174:177], v236 offset:3072
	ds_read_b128 v[178:181], v236 offset:4096
	ds_read_b128 v[182:185], v236 offset:5120
	ds_read_b128 v[186:189], v236 offset:6144
	ds_read_b128 v[190:193], v236 offset:7168
	global_load_lds_dwordx4 v210, s[22:23]
	s_add_i32 m0, s29, 0xe000
	s_nop 0
	global_load_lds_dwordx4 v212, s[22:23]
	s_waitcnt vmcnt(8) lgkmcnt(0)
	s_barrier
	s_setprio 1
	v_mfma_f32_16x16x32_bf16 v[126:129], v[130:133], v[162:165], v[126:129]
	v_mfma_f32_16x16x32_bf16 v[122:125], v[138:141], v[162:165], v[122:125]
	v_mfma_f32_16x16x32_bf16 v[114:117], v[130:133], v[170:173], v[114:117]
	v_mfma_f32_16x16x32_bf16 v[106:109], v[138:141], v[170:173], v[106:109]
	v_mfma_f32_16x16x32_bf16 v[98:101], v[130:133], v[178:181], v[98:101]
	v_mfma_f32_16x16x32_bf16 v[88:91], v[138:141], v[178:181], v[88:91]
	v_mfma_f32_16x16x32_bf16 v[80:83], v[130:133], v[186:189], v[80:83]
	v_mfma_f32_16x16x32_bf16 v[72:75], v[138:141], v[186:189], v[72:75]
	v_mfma_f32_16x16x32_bf16 v[126:129], v[134:137], v[166:169], v[126:129]
	v_mfma_f32_16x16x32_bf16 v[122:125], v[142:145], v[166:169], v[122:125]
	v_mfma_f32_16x16x32_bf16 v[114:117], v[134:137], v[174:177], v[114:117]
	v_mfma_f32_16x16x32_bf16 v[106:109], v[142:145], v[174:177], v[106:109]
	v_mfma_f32_16x16x32_bf16 v[98:101], v[134:137], v[182:185], v[98:101]
	v_mfma_f32_16x16x32_bf16 v[88:91], v[142:145], v[182:185], v[88:91]
	v_mfma_f32_16x16x32_bf16 v[80:83], v[134:137], v[190:193], v[80:83]
	v_mfma_f32_16x16x32_bf16 v[72:75], v[142:145], v[190:193], v[72:75]
	v_mfma_f32_16x16x32_bf16 v[118:121], v[146:149], v[162:165], v[118:121]
	v_mfma_f32_16x16x32_bf16 v[110:113], v[154:157], v[162:165], v[110:113]
	v_mfma_f32_16x16x32_bf16 v[102:105], v[146:149], v[170:173], v[102:105]
	v_mfma_f32_16x16x32_bf16 v[92:95], v[154:157], v[170:173], v[92:95]
	v_mfma_f32_16x16x32_bf16 v[84:87], v[146:149], v[178:181], v[84:87]
	v_mfma_f32_16x16x32_bf16 v[76:79], v[154:157], v[178:181], v[76:79]
	v_mfma_f32_16x16x32_bf16 v[68:71], v[146:149], v[186:189], v[68:71]
	v_mfma_f32_16x16x32_bf16 v[64:67], v[154:157], v[186:189], v[64:67]
	v_mfma_f32_16x16x32_bf16 v[118:121], v[150:153], v[166:169], v[118:121]
	v_mfma_f32_16x16x32_bf16 v[110:113], v[158:161], v[166:169], v[110:113]
	v_mfma_f32_16x16x32_bf16 v[102:105], v[150:153], v[174:177], v[102:105]
	v_mfma_f32_16x16x32_bf16 v[92:95], v[158:161], v[174:177], v[92:95]
	v_mfma_f32_16x16x32_bf16 v[84:87], v[150:153], v[182:185], v[84:87]
	v_mfma_f32_16x16x32_bf16 v[76:79], v[158:161], v[182:185], v[76:79]
	v_mfma_f32_16x16x32_bf16 v[68:71], v[150:153], v[190:193], v[68:71]
	v_mfma_f32_16x16x32_bf16 v[64:67], v[158:161], v[190:193], v[64:67]
	s_setprio 0
	s_barrier
	s_add_i32 s47, s47, s0
	v_lshl_add_u64 v[196:197], s[36:37], 0, v[96:97]
	s_mov_b32 m0, s47
	ds_read_b128 v[162:165], v236 offset:16384
	ds_read_b128 v[166:169], v236 offset:17408
	ds_read_b128 v[170:173], v236 offset:18432
	ds_read_b128 v[174:177], v236 offset:19456
	ds_read_b128 v[178:181], v236 offset:20480
	ds_read_b128 v[182:185], v236 offset:21504
	ds_read_b128 v[186:189], v236 offset:22528
	ds_read_b128 v[190:193], v236 offset:23552
	global_load_lds_dwordx4 v[196:197], off
	s_add_i32 m0, s47, 0x2000
	s_add_u32 s62, s36, 0x80000
	v_lshl_add_u64 v[198:199], s[36:37], 0, v[208:209]
	s_addc_u32 s63, s37, 0
	s_add_i32 s47, s50, s0
	global_load_lds_dwordx4 v[198:199], off
	s_mov_b32 m0, s47
	v_lshl_add_u64 v[202:203], s[38:39], 0, v[206:207]
	global_load_lds_dwordx4 v96, s[62:63]
	s_add_i32 m0, s47, 0x2000
	s_nop 0
	global_load_lds_dwordx4 v208, s[62:63]
	s_mov_b32 m0, s29
	v_lshl_add_u64 v[200:201], s[38:39], 0, v[204:205]
	global_load_lds_dwordx4 v[200:201], off
	s_mov_b32 m0, s30
	s_nop 0
	global_load_lds_dwordx4 v[202:203], off
	s_waitcnt vmcnt(8) lgkmcnt(0)
	s_barrier
	s_setprio 1
	v_mfma_f32_16x16x32_bf16 v[60:63], v[130:133], v[162:165], v[60:63]
	v_mfma_f32_16x16x32_bf16 v[56:59], v[138:141], v[162:165], v[56:59]
	v_mfma_f32_16x16x32_bf16 v[48:51], v[130:133], v[170:173], v[48:51]
	v_mfma_f32_16x16x32_bf16 v[40:43], v[138:141], v[170:173], v[40:43]
	v_mfma_f32_16x16x32_bf16 v[32:35], v[130:133], v[178:181], v[32:35]
	v_mfma_f32_16x16x32_bf16 v[24:27], v[138:141], v[178:181], v[24:27]
	v_mfma_f32_16x16x32_bf16 v[16:19], v[130:133], v[186:189], v[16:19]
	v_mfma_f32_16x16x32_bf16 v[8:11], v[138:141], v[186:189], v[8:11]
	v_mfma_f32_16x16x32_bf16 v[60:63], v[134:137], v[166:169], v[60:63]
	v_mfma_f32_16x16x32_bf16 v[56:59], v[142:145], v[166:169], v[56:59]
	v_mfma_f32_16x16x32_bf16 v[48:51], v[134:137], v[174:177], v[48:51]
	v_mfma_f32_16x16x32_bf16 v[40:43], v[142:145], v[174:177], v[40:43]
	v_mfma_f32_16x16x32_bf16 v[32:35], v[134:137], v[182:185], v[32:35]
	v_mfma_f32_16x16x32_bf16 v[24:27], v[142:145], v[182:185], v[24:27]
	v_mfma_f32_16x16x32_bf16 v[16:19], v[134:137], v[190:193], v[16:19]
	v_mfma_f32_16x16x32_bf16 v[8:11], v[142:145], v[190:193], v[8:11]
	v_mfma_f32_16x16x32_bf16 v[52:55], v[146:149], v[162:165], v[52:55]
	v_mfma_f32_16x16x32_bf16 v[44:47], v[154:157], v[162:165], v[44:47]
	v_mfma_f32_16x16x32_bf16 v[36:39], v[146:149], v[170:173], v[36:39]
	v_mfma_f32_16x16x32_bf16 v[28:31], v[154:157], v[170:173], v[28:31]
	v_mfma_f32_16x16x32_bf16 v[20:23], v[146:149], v[178:181], v[20:23]
	v_mfma_f32_16x16x32_bf16 v[12:15], v[154:157], v[178:181], v[12:15]
	v_mfma_f32_16x16x32_bf16 v[4:7], v[146:149], v[186:189], v[4:7]
	v_mfma_f32_16x16x32_bf16 v[0:3], v[154:157], v[186:189], v[0:3]
	v_mfma_f32_16x16x32_bf16 v[52:55], v[150:153], v[166:169], v[52:55]
	v_mfma_f32_16x16x32_bf16 v[44:47], v[158:161], v[166:169], v[44:47]
	v_mfma_f32_16x16x32_bf16 v[36:39], v[150:153], v[174:177], v[36:39]
	v_mfma_f32_16x16x32_bf16 v[28:31], v[158:161], v[174:177], v[28:31]
	v_mfma_f32_16x16x32_bf16 v[20:23], v[150:153], v[182:185], v[20:23]
	v_mfma_f32_16x16x32_bf16 v[12:15], v[158:161], v[182:185], v[12:15]
	v_mfma_f32_16x16x32_bf16 v[4:7], v[150:153], v[190:193], v[4:7]
	v_mfma_f32_16x16x32_bf16 v[0:3], v[158:161], v[190:193], v[0:3]
	s_setprio 0
	s_barrier
	s_add_i32 s47, 0, 0x18000
	s_add_i32 s50, 0, 0x1c000
	v_add_u32_e32 v142, s47, v234
	v_add_u32_e32 v158, s50, v234
	ds_read_b128 v[130:133], v142
	ds_read_b128 v[134:137], v142 offset:1024
	ds_read_b128 v[138:141], v142 offset:2048
	ds_read_b128 v[142:145], v142 offset:3072
	ds_read_b128 v[146:149], v158
	ds_read_b128 v[150:153], v158 offset:1024
	ds_read_b128 v[154:157], v158 offset:2048
	ds_read_b128 v[158:161], v158 offset:3072
	s_add_u32 s38, s38, 0x80000
	s_addc_u32 s39, s39, 0
	s_mov_b32 m0, s31
	ds_read_b128 v[162:165], v236 offset:32768
	ds_read_b128 v[166:169], v236 offset:33792
	ds_read_b128 v[170:173], v236 offset:34816
	ds_read_b128 v[174:177], v236 offset:35840
	ds_read_b128 v[178:181], v236 offset:36864
	ds_read_b128 v[182:185], v236 offset:37888
	ds_read_b128 v[186:189], v236 offset:38912
	ds_read_b128 v[190:193], v236 offset:39936
	global_load_lds_dwordx4 v204, s[38:39]
	s_mov_b32 m0, s40
	s_nop 0
	global_load_lds_dwordx4 v206, s[38:39]
	s_waitcnt vmcnt(8) lgkmcnt(0)
	s_barrier
	s_setprio 1
	v_mfma_f32_16x16x32_bf16 v[126:129], v[130:133], v[162:165], v[126:129]
	v_mfma_f32_16x16x32_bf16 v[122:125], v[138:141], v[162:165], v[122:125]
	v_mfma_f32_16x16x32_bf16 v[114:117], v[130:133], v[170:173], v[114:117]
	v_mfma_f32_16x16x32_bf16 v[106:109], v[138:141], v[170:173], v[106:109]
	v_mfma_f32_16x16x32_bf16 v[98:101], v[130:133], v[178:181], v[98:101]
	v_mfma_f32_16x16x32_bf16 v[88:91], v[138:141], v[178:181], v[88:91]
	v_mfma_f32_16x16x32_bf16 v[80:83], v[130:133], v[186:189], v[80:83]
	v_mfma_f32_16x16x32_bf16 v[72:75], v[138:141], v[186:189], v[72:75]
	v_mfma_f32_16x16x32_bf16 v[126:129], v[134:137], v[166:169], v[126:129]
	v_mfma_f32_16x16x32_bf16 v[122:125], v[142:145], v[166:169], v[122:125]
	v_mfma_f32_16x16x32_bf16 v[114:117], v[134:137], v[174:177], v[114:117]
	v_mfma_f32_16x16x32_bf16 v[106:109], v[142:145], v[174:177], v[106:109]
	v_mfma_f32_16x16x32_bf16 v[98:101], v[134:137], v[182:185], v[98:101]
	v_mfma_f32_16x16x32_bf16 v[88:91], v[142:145], v[182:185], v[88:91]
	v_mfma_f32_16x16x32_bf16 v[80:83], v[134:137], v[190:193], v[80:83]
	v_mfma_f32_16x16x32_bf16 v[72:75], v[142:145], v[190:193], v[72:75]
	v_mfma_f32_16x16x32_bf16 v[118:121], v[146:149], v[162:165], v[118:121]
	v_mfma_f32_16x16x32_bf16 v[110:113], v[154:157], v[162:165], v[110:113]
	v_mfma_f32_16x16x32_bf16 v[102:105], v[146:149], v[170:173], v[102:105]
	v_mfma_f32_16x16x32_bf16 v[92:95], v[154:157], v[170:173], v[92:95]
	v_mfma_f32_16x16x32_bf16 v[84:87], v[146:149], v[178:181], v[84:87]
	v_mfma_f32_16x16x32_bf16 v[76:79], v[154:157], v[178:181], v[76:79]
	v_mfma_f32_16x16x32_bf16 v[68:71], v[146:149], v[186:189], v[68:71]
	v_mfma_f32_16x16x32_bf16 v[64:67], v[154:157], v[186:189], v[64:67]
	v_mfma_f32_16x16x32_bf16 v[118:121], v[150:153], v[166:169], v[118:121]
	v_mfma_f32_16x16x32_bf16 v[110:113], v[158:161], v[166:169], v[110:113]
	v_mfma_f32_16x16x32_bf16 v[102:105], v[150:153], v[174:177], v[102:105]
	v_mfma_f32_16x16x32_bf16 v[92:95], v[158:161], v[174:177], v[92:95]
	v_mfma_f32_16x16x32_bf16 v[84:87], v[150:153], v[182:185], v[84:87]
	v_mfma_f32_16x16x32_bf16 v[76:79], v[158:161], v[182:185], v[76:79]
	v_mfma_f32_16x16x32_bf16 v[68:71], v[150:153], v[190:193], v[68:71]
	v_mfma_f32_16x16x32_bf16 v[64:67], v[158:161], v[190:193], v[64:67]
	s_setprio 0
	s_barrier
	s_add_i32 s38, s47, s0
	v_lshl_add_u64 v[196:197], v[196:197], 0, s[82:83]
	s_mov_b32 m0, s38
	ds_read_b128 v[162:165], v236 offset:49152
	ds_read_b128 v[166:169], v236 offset:50176
	ds_read_b128 v[170:173], v236 offset:51200
	ds_read_b128 v[174:177], v236 offset:52224
	ds_read_b128 v[178:181], v236 offset:53248
	ds_read_b128 v[182:185], v236 offset:54272
	ds_read_b128 v[186:189], v236 offset:55296
	ds_read_b128 v[190:193], v236 offset:56320
	global_load_lds_dwordx4 v[196:197], off
	s_add_i32 m0, s38, 0x2000
	s_add_u32 s36, s36, 0x80080
	v_lshl_add_u64 v[196:197], v[198:199], 0, s[82:83]
	s_addc_u32 s37, s37, 0
	s_add_i32 s38, s50, s0
	global_load_lds_dwordx4 v[196:197], off
	s_mov_b32 m0, s38
	s_nop 0
	global_load_lds_dwordx4 v96, s[36:37]
	s_add_i32 m0, s38, 0x2000
	s_nop 0
	global_load_lds_dwordx4 v208, s[36:37]
	s_mov_b32 m0, s45
	v_lshl_add_u64 v[196:197], v[200:201], 0, s[82:83]
	global_load_lds_dwordx4 v[196:197], off
	s_mov_b32 m0, s48
	v_lshl_add_u64 v[196:197], v[202:203], 0, s[82:83]
	global_load_lds_dwordx4 v[196:197], off
	s_waitcnt vmcnt(8) lgkmcnt(0)
	s_barrier
	s_setprio 1
	v_mfma_f32_16x16x32_bf16 v[60:63], v[130:133], v[162:165], v[60:63]
	v_mfma_f32_16x16x32_bf16 v[56:59], v[138:141], v[162:165], v[56:59]
	v_mfma_f32_16x16x32_bf16 v[48:51], v[130:133], v[170:173], v[48:51]
	v_mfma_f32_16x16x32_bf16 v[40:43], v[138:141], v[170:173], v[40:43]
	v_mfma_f32_16x16x32_bf16 v[32:35], v[130:133], v[178:181], v[32:35]
	v_mfma_f32_16x16x32_bf16 v[24:27], v[138:141], v[178:181], v[24:27]
	v_mfma_f32_16x16x32_bf16 v[16:19], v[130:133], v[186:189], v[16:19]
	v_mfma_f32_16x16x32_bf16 v[8:11], v[138:141], v[186:189], v[8:11]
	v_mfma_f32_16x16x32_bf16 v[60:63], v[134:137], v[166:169], v[60:63]
	v_mfma_f32_16x16x32_bf16 v[56:59], v[142:145], v[166:169], v[56:59]
	v_mfma_f32_16x16x32_bf16 v[48:51], v[134:137], v[174:177], v[48:51]
	v_mfma_f32_16x16x32_bf16 v[40:43], v[142:145], v[174:177], v[40:43]
	v_mfma_f32_16x16x32_bf16 v[32:35], v[134:137], v[182:185], v[32:35]
	v_mfma_f32_16x16x32_bf16 v[24:27], v[142:145], v[182:185], v[24:27]
	v_mfma_f32_16x16x32_bf16 v[16:19], v[134:137], v[190:193], v[16:19]
	v_mfma_f32_16x16x32_bf16 v[8:11], v[142:145], v[190:193], v[8:11]
	v_mfma_f32_16x16x32_bf16 v[52:55], v[146:149], v[162:165], v[52:55]
	v_mfma_f32_16x16x32_bf16 v[44:47], v[154:157], v[162:165], v[44:47]
	v_mfma_f32_16x16x32_bf16 v[36:39], v[146:149], v[170:173], v[36:39]
	v_mfma_f32_16x16x32_bf16 v[28:31], v[154:157], v[170:173], v[28:31]
	v_mfma_f32_16x16x32_bf16 v[20:23], v[146:149], v[178:181], v[20:23]
	v_mfma_f32_16x16x32_bf16 v[12:15], v[154:157], v[178:181], v[12:15]
	v_mfma_f32_16x16x32_bf16 v[4:7], v[146:149], v[186:189], v[4:7]
	v_mfma_f32_16x16x32_bf16 v[0:3], v[154:157], v[186:189], v[0:3]
	v_mfma_f32_16x16x32_bf16 v[52:55], v[150:153], v[166:169], v[52:55]
	v_mfma_f32_16x16x32_bf16 v[44:47], v[158:161], v[166:169], v[44:47]
	v_mfma_f32_16x16x32_bf16 v[36:39], v[150:153], v[174:177], v[36:39]
	v_mfma_f32_16x16x32_bf16 v[28:31], v[158:161], v[174:177], v[28:31]
	v_mfma_f32_16x16x32_bf16 v[20:23], v[150:153], v[182:185], v[20:23]
	v_mfma_f32_16x16x32_bf16 v[12:15], v[158:161], v[182:185], v[12:15]
	v_mfma_f32_16x16x32_bf16 v[4:7], v[150:153], v[190:193], v[4:7]
	v_mfma_f32_16x16x32_bf16 v[0:3], v[158:161], v[190:193], v[0:3]
	s_setprio 0
	s_barrier
	s_add_u32 s22, s22, 0x100
	s_addc_u32 s23, s23, 0
	s_add_u32 s57, s57, 0x100
	s_addc_u32 s58, s58, 0
	s_cmp_ge_i32 s46, s15
	s_mov_b32 s38, s46
	s_cbranch_scc0 .LBB0_736
	s_and_b64 vcc, exec, s[10:11]
	s_cbranch_vccz .LBB0_739
	s_barrier

.LBB0_877:
	s_lshl_b32 s5, s5, 5
	s_and_b32 s5, s5, 0x60
	s_add_i32 m0, s30, 0x18000
	v_lshl_add_u64 v[6:7], v[6:7], 0, s[82:83]
	s_lshl_b32 s11, s4, 13
	s_lshl_b32 s16, s5, 7
	s_waitcnt vmcnt(2)
	s_barrier
	global_load_lds_dwordx4 v[6:7], off
	v_lshl_add_u64 v[4:5], v[4:5], 0, s[82:83]
	s_add_i32 m0, s30, 0x1a000
	s_add_i32 s48, s30, 0x8000
	s_add_i32 s49, s30, 0xa000
	global_load_lds_dwordx4 v[4:5], off
	v_lshl_add_u64 v[0:1], v[0:1], 0, s[82:83]
	s_mov_b32 m0, s48
	s_add_u32 s12, s38, 0x80080
	global_load_lds_dwordx4 v[0:1], off
	v_lshl_add_u64 v[0:1], v[2:3], 0, s[82:83]
	s_mov_b32 m0, s49
	s_addc_u32 s13, s39, 0
	global_load_lds_dwordx4 v[0:1], off
	s_add_i32 m0, s30, 0x1c000
	s_nop 0
	global_load_lds_dwordx4 v132, s[12:13]
	s_add_i32 m0, s30, 0x1e000
	s_cmpk_lt_u32 s10, 0x100
	global_load_lds_dwordx4 v136, s[12:13]
	v_lshrrev_b32_e32 v0, 1, v8
	v_and_b32_e32 v0, 24, v0
	v_and_b32_e32 v1, 15, v8
	v_lshlrev_b32_e32 v2, 1, v0
	v_lshl_or_b32 v144, s4, 6, v1
	v_lshl_or_b32 v1, v1, 6, v2
	v_lshlrev_b32_e32 v2, 2, v8
	v_and_b32_e32 v2, 32, v2
	v_bitop3_b32 v3, v1, s11, v2 bitop3:0xde
	v_bitop3_b32 v145, v1, s16, v2 bitop3:0xde
	v_lshlrev_b32_e32 v1, 15, v9
	v_and_b32_e32 v1, 0xffff0000, v1
	v_lshl_add_u32 v1, v10, 12, v1
	v_and_b32_e32 v2, 1, v9
	v_lshl_or_b32 v1, v2, 6, v1
	v_lshl_add_u32 v138, v11, 1, v1
	v_lshlrev_b32_e32 v1, 15, v12
	v_and_b32_e32 v1, 0xffff0000, v1
	s_waitcnt vmcnt(6)
	v_lshl_add_u32 v1, v13, 12, v1
	v_and_b32_e32 v2, 1, v12
	v_lshl_or_b32 v1, v2, 6, v1
	s_cselect_b64 s[10:11], -1, 0
	s_bfe_i64 s[12:13], s[92:93], 0x200000
	v_mov_b32_e32 v139, v97
	v_lshl_add_u32 v140, v14, 1, v1
	v_mov_b32_e32 v141, v97
	s_mov_b32 s52, 0
	v_add_u32_e32 v146, 0, v3
	s_lshl_b32 s92, s5, 1
	v_lshlrev_b32_e32 v96, 1, v0
	s_mov_b64 s[22:23], s[38:39]
	s_mov_b64 s[20:21], s[36:37]
	s_barrier
	s_branch .LBB0_880

.LBB0_890:
	s_add_i32 s46, s40, 2
	s_add_u32 s38, s36, 0xfff80080
	s_addc_u32 s39, s37, -1
	s_add_i32 s47, 0, 0x10000
	s_cmp_eq_u32 s42, s40
	s_cselect_b32 s41, s21, s39
	s_cselect_b32 s40, s20, s38
	v_add_u32_e32 v142, s47, v145
	s_cselect_b32 s39, s23, s56
	s_cselect_b32 s38, s22, s43
	s_add_i32 s50, 0, 0x14000
	ds_read_b128 v[148:151], v142
	ds_read_b128 v[152:155], v142 offset:1024
	ds_read_b128 v[156:159], v142 offset:2048
	ds_read_b128 v[160:163], v142 offset:3072
	v_add_u32_e32 v142, s50, v145
	ds_read_b128 v[164:167], v142
	ds_read_b128 v[168:171], v142 offset:1024
	ds_read_b128 v[172:175], v142 offset:2048
	ds_read_b128 v[176:179], v142 offset:3072
	s_add_i32 m0, s30, 0xc000
	ds_read_b128 v[180:183], v146
	ds_read_b128 v[184:187], v146 offset:1024
	ds_read_b128 v[188:191], v146 offset:2048
	ds_read_b128 v[196:199], v146 offset:3072
	ds_read_b128 v[200:203], v146 offset:4096
	ds_read_b128 v[204:207], v146 offset:5120
	ds_read_b128 v[208:211], v146 offset:6144
	ds_read_b128 v[212:215], v146 offset:7168
	global_load_lds_dwordx4 v138, s[36:37]
	s_add_i32 m0, s30, 0xe000
	s_nop 0
	global_load_lds_dwordx4 v140, s[36:37]
	s_waitcnt vmcnt(8) lgkmcnt(0)
	s_barrier
	s_setprio 1
	v_mfma_f32_16x16x32_bf16 v[126:129], v[148:151], v[180:183], v[126:129]
	v_mfma_f32_16x16x32_bf16 v[122:125], v[156:159], v[180:183], v[122:125]
	v_mfma_f32_16x16x32_bf16 v[118:121], v[148:151], v[188:191], v[118:121]
	v_mfma_f32_16x16x32_bf16 v[110:113], v[156:159], v[188:191], v[110:113]
	v_mfma_f32_16x16x32_bf16 v[102:105], v[148:151], v[200:203], v[102:105]
	v_mfma_f32_16x16x32_bf16 v[92:95], v[156:159], v[200:203], v[92:95]
	v_mfma_f32_16x16x32_bf16 v[84:87], v[148:151], v[208:211], v[84:87]
	v_mfma_f32_16x16x32_bf16 v[76:79], v[156:159], v[208:211], v[76:79]
	v_mfma_f32_16x16x32_bf16 v[126:129], v[152:155], v[184:187], v[126:129]
	v_mfma_f32_16x16x32_bf16 v[122:125], v[160:163], v[184:187], v[122:125]
	v_mfma_f32_16x16x32_bf16 v[118:121], v[152:155], v[196:199], v[118:121]
	v_mfma_f32_16x16x32_bf16 v[110:113], v[160:163], v[196:199], v[110:113]
	v_mfma_f32_16x16x32_bf16 v[102:105], v[152:155], v[204:207], v[102:105]
	v_mfma_f32_16x16x32_bf16 v[92:95], v[160:163], v[204:207], v[92:95]
	v_mfma_f32_16x16x32_bf16 v[84:87], v[152:155], v[212:215], v[84:87]
	v_mfma_f32_16x16x32_bf16 v[76:79], v[160:163], v[212:215], v[76:79]
	v_mfma_f32_16x16x32_bf16 v[114:117], v[164:167], v[180:183], v[114:117]
	v_mfma_f32_16x16x32_bf16 v[106:109], v[172:175], v[180:183], v[106:109]
	v_mfma_f32_16x16x32_bf16 v[98:101], v[164:167], v[188:191], v[98:101]
	v_mfma_f32_16x16x32_bf16 v[88:91], v[172:175], v[188:191], v[88:91]
	v_mfma_f32_16x16x32_bf16 v[80:83], v[164:167], v[200:203], v[80:83]
	v_mfma_f32_16x16x32_bf16 v[72:75], v[172:175], v[200:203], v[72:75]
	v_mfma_f32_16x16x32_bf16 v[68:71], v[164:167], v[208:211], v[68:71]
	v_mfma_f32_16x16x32_bf16 v[64:67], v[172:175], v[208:211], v[64:67]
	v_mfma_f32_16x16x32_bf16 v[114:117], v[168:171], v[184:187], v[114:117]
	v_mfma_f32_16x16x32_bf16 v[106:109], v[176:179], v[184:187], v[106:109]
	v_mfma_f32_16x16x32_bf16 v[98:101], v[168:171], v[196:199], v[98:101]
	v_mfma_f32_16x16x32_bf16 v[88:91], v[176:179], v[196:199], v[88:91]
	v_mfma_f32_16x16x32_bf16 v[80:83], v[168:171], v[204:207], v[80:83]
	v_mfma_f32_16x16x32_bf16 v[72:75], v[176:179], v[204:207], v[72:75]
	v_mfma_f32_16x16x32_bf16 v[68:71], v[168:171], v[212:215], v[68:71]
	v_mfma_f32_16x16x32_bf16 v[64:67], v[176:179], v[212:215], v[64:67]
	s_setprio 0
	s_barrier
	s_add_i32 s47, s47, s15
	v_lshl_add_u64 v[142:143], s[38:39], 0, v[132:133]
	s_mov_b32 m0, s47
	ds_read_b128 v[180:183], v146 offset:16384
	ds_read_b128 v[184:187], v146 offset:17408
	ds_read_b128 v[188:191], v146 offset:18432
	ds_read_b128 v[196:199], v146 offset:19456
	ds_read_b128 v[200:203], v146 offset:20480
	ds_read_b128 v[204:207], v146 offset:21504
	ds_read_b128 v[208:211], v146 offset:22528
	ds_read_b128 v[212:215], v146 offset:23552
	global_load_lds_dwordx4 v[142:143], off
	s_add_i32 m0, s47, 0x2000
	s_add_u32 s58, s38, 0x80000
	v_lshl_add_u64 v[192:193], s[38:39], 0, v[136:137]
	s_addc_u32 s59, s39, 0
	s_add_i32 s47, s50, s15
	global_load_lds_dwordx4 v[192:193], off
	s_mov_b32 m0, s47
	v_lshl_add_u64 v[218:219], s[40:41], 0, v[134:135]
	global_load_lds_dwordx4 v132, s[58:59]
	s_add_i32 m0, s47, 0x2000
	s_nop 0
	global_load_lds_dwordx4 v136, s[58:59]
	s_mov_b32 m0, s30
	v_lshl_add_u64 v[216:217], s[40:41], 0, v[130:131]
	global_load_lds_dwordx4 v[216:217], off
	s_mov_b32 m0, s31
	s_nop 0
	global_load_lds_dwordx4 v[218:219], off
	s_waitcnt vmcnt(8) lgkmcnt(0)
	s_barrier
	s_setprio 1
	v_mfma_f32_16x16x32_bf16 v[60:63], v[148:151], v[180:183], v[60:63]
	v_mfma_f32_16x16x32_bf16 v[56:59], v[156:159], v[180:183], v[56:59]
	v_mfma_f32_16x16x32_bf16 v[52:55], v[148:151], v[188:191], v[52:55]
	v_mfma_f32_16x16x32_bf16 v[44:47], v[156:159], v[188:191], v[44:47]
	v_mfma_f32_16x16x32_bf16 v[36:39], v[148:151], v[200:203], v[36:39]
	v_mfma_f32_16x16x32_bf16 v[28:31], v[156:159], v[200:203], v[28:31]
	v_mfma_f32_16x16x32_bf16 v[20:23], v[148:151], v[208:211], v[20:23]
	v_mfma_f32_16x16x32_bf16 v[12:15], v[156:159], v[208:211], v[12:15]
	v_mfma_f32_16x16x32_bf16 v[60:63], v[152:155], v[184:187], v[60:63]
	v_mfma_f32_16x16x32_bf16 v[56:59], v[160:163], v[184:187], v[56:59]
	v_mfma_f32_16x16x32_bf16 v[52:55], v[152:155], v[196:199], v[52:55]
	v_mfma_f32_16x16x32_bf16 v[44:47], v[160:163], v[196:199], v[44:47]
	v_mfma_f32_16x16x32_bf16 v[36:39], v[152:155], v[204:207], v[36:39]
	v_mfma_f32_16x16x32_bf16 v[28:31], v[160:163], v[204:207], v[28:31]
	v_mfma_f32_16x16x32_bf16 v[20:23], v[152:155], v[212:215], v[20:23]
	v_mfma_f32_16x16x32_bf16 v[12:15], v[160:163], v[212:215], v[12:15]
	v_mfma_f32_16x16x32_bf16 v[48:51], v[164:167], v[180:183], v[48:51]
	v_mfma_f32_16x16x32_bf16 v[40:43], v[172:175], v[180:183], v[40:43]
	v_mfma_f32_16x16x32_bf16 v[32:35], v[164:167], v[188:191], v[32:35]
	v_mfma_f32_16x16x32_bf16 v[24:27], v[172:175], v[188:191], v[24:27]
	v_mfma_f32_16x16x32_bf16 v[16:19], v[164:167], v[200:203], v[16:19]
	v_mfma_f32_16x16x32_bf16 v[8:11], v[172:175], v[200:203], v[8:11]
	v_mfma_f32_16x16x32_bf16 v[4:7], v[164:167], v[208:211], v[4:7]
	v_mfma_f32_16x16x32_bf16 v[0:3], v[172:175], v[208:211], v[0:3]
	v_mfma_f32_16x16x32_bf16 v[48:51], v[168:171], v[184:187], v[48:51]
	v_mfma_f32_16x16x32_bf16 v[40:43], v[176:179], v[184:187], v[40:43]
	v_mfma_f32_16x16x32_bf16 v[32:35], v[168:171], v[196:199], v[32:35]
	v_mfma_f32_16x16x32_bf16 v[24:27], v[176:179], v[196:199], v[24:27]
	v_mfma_f32_16x16x32_bf16 v[16:19], v[168:171], v[204:207], v[16:19]
	v_mfma_f32_16x16x32_bf16 v[8:11], v[176:179], v[204:207], v[8:11]
	v_mfma_f32_16x16x32_bf16 v[4:7], v[168:171], v[212:215], v[4:7]
	v_mfma_f32_16x16x32_bf16 v[0:3], v[176:179], v[212:215], v[0:3]
	s_setprio 0
	s_barrier
	s_add_i32 s47, 0, 0x18000
	v_add_u32_e32 v147, s47, v145
	s_add_i32 s50, 0, 0x1c000
	ds_read_b128 v[148:151], v147
	ds_read_b128 v[152:155], v147 offset:1024
	ds_read_b128 v[156:159], v147 offset:2048
	ds_read_b128 v[160:163], v147 offset:3072
	v_add_u32_e32 v147, s50, v145
	ds_read_b128 v[164:167], v147
	ds_read_b128 v[168:171], v147 offset:1024
	ds_read_b128 v[172:175], v147 offset:2048
	ds_read_b128 v[176:179], v147 offset:3072
	s_add_u32 s40, s40, 0x80000
	s_addc_u32 s41, s41, 0
	s_mov_b32 m0, s44
	ds_read_b128 v[180:183], v146 offset:32768
	ds_read_b128 v[184:187], v146 offset:33792
	ds_read_b128 v[188:191], v146 offset:34816
	ds_read_b128 v[196:199], v146 offset:35840
	ds_read_b128 v[200:203], v146 offset:36864
	ds_read_b128 v[204:207], v146 offset:37888
	ds_read_b128 v[208:211], v146 offset:38912
	ds_read_b128 v[212:215], v146 offset:39936
	global_load_lds_dwordx4 v130, s[40:41]
	s_mov_b32 m0, s45
	s_nop 0
	global_load_lds_dwordx4 v134, s[40:41]
	s_waitcnt vmcnt(8) lgkmcnt(0)
	s_barrier
	s_setprio 1
	v_mfma_f32_16x16x32_bf16 v[126:129], v[148:151], v[180:183], v[126:129]
	v_mfma_f32_16x16x32_bf16 v[122:125], v[156:159], v[180:183], v[122:125]
	v_mfma_f32_16x16x32_bf16 v[118:121], v[148:151], v[188:191], v[118:121]
	v_mfma_f32_16x16x32_bf16 v[110:113], v[156:159], v[188:191], v[110:113]
	v_mfma_f32_16x16x32_bf16 v[102:105], v[148:151], v[200:203], v[102:105]
	v_mfma_f32_16x16x32_bf16 v[92:95], v[156:159], v[200:203], v[92:95]
	v_mfma_f32_16x16x32_bf16 v[84:87], v[148:151], v[208:211], v[84:87]
	v_mfma_f32_16x16x32_bf16 v[76:79], v[156:159], v[208:211], v[76:79]
	v_mfma_f32_16x16x32_bf16 v[126:129], v[152:155], v[184:187], v[126:129]
	v_mfma_f32_16x16x32_bf16 v[122:125], v[160:163], v[184:187], v[122:125]
	v_mfma_f32_16x16x32_bf16 v[118:121], v[152:155], v[196:199], v[118:121]
	v_mfma_f32_16x16x32_bf16 v[110:113], v[160:163], v[196:199], v[110:113]
	v_mfma_f32_16x16x32_bf16 v[102:105], v[152:155], v[204:207], v[102:105]
	v_mfma_f32_16x16x32_bf16 v[92:95], v[160:163], v[204:207], v[92:95]
	v_mfma_f32_16x16x32_bf16 v[84:87], v[152:155], v[212:215], v[84:87]
	v_mfma_f32_16x16x32_bf16 v[76:79], v[160:163], v[212:215], v[76:79]
	v_mfma_f32_16x16x32_bf16 v[114:117], v[164:167], v[180:183], v[114:117]
	v_mfma_f32_16x16x32_bf16 v[106:109], v[172:175], v[180:183], v[106:109]
	v_mfma_f32_16x16x32_bf16 v[98:101], v[164:167], v[188:191], v[98:101]
	v_mfma_f32_16x16x32_bf16 v[88:91], v[172:175], v[188:191], v[88:91]
	v_mfma_f32_16x16x32_bf16 v[80:83], v[164:167], v[200:203], v[80:83]
	v_mfma_f32_16x16x32_bf16 v[72:75], v[172:175], v[200:203], v[72:75]
	v_mfma_f32_16x16x32_bf16 v[68:71], v[164:167], v[208:211], v[68:71]
	v_mfma_f32_16x16x32_bf16 v[64:67], v[172:175], v[208:211], v[64:67]
	v_mfma_f32_16x16x32_bf16 v[114:117], v[168:171], v[184:187], v[114:117]
	v_mfma_f32_16x16x32_bf16 v[106:109], v[176:179], v[184:187], v[106:109]
	v_mfma_f32_16x16x32_bf16 v[98:101], v[168:171], v[196:199], v[98:101]
	v_mfma_f32_16x16x32_bf16 v[88:91], v[176:179], v[196:199], v[88:91]
	v_mfma_f32_16x16x32_bf16 v[80:83], v[168:171], v[204:207], v[80:83]
	v_mfma_f32_16x16x32_bf16 v[72:75], v[176:179], v[204:207], v[72:75]
	v_mfma_f32_16x16x32_bf16 v[68:71], v[168:171], v[212:215], v[68:71]
	v_mfma_f32_16x16x32_bf16 v[64:67], v[176:179], v[212:215], v[64:67]
	s_setprio 0
	s_barrier
	s_add_i32 s40, s47, s15
	v_lshl_add_u64 v[142:143], v[142:143], 0, s[82:83]
	s_mov_b32 m0, s40
	ds_read_b128 v[180:183], v146 offset:49152
	ds_read_b128 v[184:187], v146 offset:50176
	ds_read_b128 v[188:191], v146 offset:51200
	ds_read_b128 v[196:199], v146 offset:52224
	ds_read_b128 v[200:203], v146 offset:53248
	ds_read_b128 v[204:207], v146 offset:54272
	ds_read_b128 v[208:211], v146 offset:55296
	ds_read_b128 v[212:215], v146 offset:56320
	global_load_lds_dwordx4 v[142:143], off
	s_add_i32 m0, s40, 0x2000
	s_add_u32 s38, s38, 0x80080
	v_lshl_add_u64 v[142:143], v[192:193], 0, s[82:83]
	s_addc_u32 s39, s39, 0
	s_add_i32 s40, s50, s15
	global_load_lds_dwordx4 v[142:143], off
	s_mov_b32 m0, s40
	s_nop 0
	global_load_lds_dwordx4 v132, s[38:39]
	s_add_i32 m0, s40, 0x2000
	s_nop 0
	global_load_lds_dwordx4 v136, s[38:39]
	s_mov_b32 m0, s48
	v_lshl_add_u64 v[142:143], v[216:217], 0, s[82:83]
	global_load_lds_dwordx4 v[142:143], off
	s_mov_b32 m0, s49
	v_lshl_add_u64 v[142:143], v[218:219], 0, s[82:83]
	global_load_lds_dwordx4 v[142:143], off
	s_waitcnt vmcnt(8) lgkmcnt(0)
	s_barrier
	s_setprio 1
	v_mfma_f32_16x16x32_bf16 v[60:63], v[148:151], v[180:183], v[60:63]
	v_mfma_f32_16x16x32_bf16 v[56:59], v[156:159], v[180:183], v[56:59]
	v_mfma_f32_16x16x32_bf16 v[52:55], v[148:151], v[188:191], v[52:55]
	v_mfma_f32_16x16x32_bf16 v[44:47], v[156:159], v[188:191], v[44:47]
	v_mfma_f32_16x16x32_bf16 v[36:39], v[148:151], v[200:203], v[36:39]
	v_mfma_f32_16x16x32_bf16 v[28:31], v[156:159], v[200:203], v[28:31]
	v_mfma_f32_16x16x32_bf16 v[20:23], v[148:151], v[208:211], v[20:23]
	v_mfma_f32_16x16x32_bf16 v[12:15], v[156:159], v[208:211], v[12:15]
	v_mfma_f32_16x16x32_bf16 v[60:63], v[152:155], v[184:187], v[60:63]
	v_mfma_f32_16x16x32_bf16 v[56:59], v[160:163], v[184:187], v[56:59]
	v_mfma_f32_16x16x32_bf16 v[52:55], v[152:155], v[196:199], v[52:55]
	v_mfma_f32_16x16x32_bf16 v[44:47], v[160:163], v[196:199], v[44:47]
	v_mfma_f32_16x16x32_bf16 v[36:39], v[152:155], v[204:207], v[36:39]
	v_mfma_f32_16x16x32_bf16 v[28:31], v[160:163], v[204:207], v[28:31]
	v_mfma_f32_16x16x32_bf16 v[20:23], v[152:155], v[212:215], v[20:23]
	v_mfma_f32_16x16x32_bf16 v[12:15], v[160:163], v[212:215], v[12:15]
	v_mfma_f32_16x16x32_bf16 v[48:51], v[164:167], v[180:183], v[48:51]
	v_mfma_f32_16x16x32_bf16 v[40:43], v[172:175], v[180:183], v[40:43]
	v_mfma_f32_16x16x32_bf16 v[32:35], v[164:167], v[188:191], v[32:35]
	v_mfma_f32_16x16x32_bf16 v[24:27], v[172:175], v[188:191], v[24:27]
	v_mfma_f32_16x16x32_bf16 v[16:19], v[164:167], v[200:203], v[16:19]
	v_mfma_f32_16x16x32_bf16 v[8:11], v[172:175], v[200:203], v[8:11]
	v_mfma_f32_16x16x32_bf16 v[4:7], v[164:167], v[208:211], v[4:7]
	v_mfma_f32_16x16x32_bf16 v[0:3], v[172:175], v[208:211], v[0:3]
	v_mfma_f32_16x16x32_bf16 v[48:51], v[168:171], v[184:187], v[48:51]
	v_mfma_f32_16x16x32_bf16 v[40:43], v[176:179], v[184:187], v[40:43]
	v_mfma_f32_16x16x32_bf16 v[32:35], v[168:171], v[196:199], v[32:35]
	v_mfma_f32_16x16x32_bf16 v[24:27], v[176:179], v[196:199], v[24:27]
	v_mfma_f32_16x16x32_bf16 v[16:19], v[168:171], v[204:207], v[16:19]
	v_mfma_f32_16x16x32_bf16 v[8:11], v[176:179], v[204:207], v[8:11]
	v_mfma_f32_16x16x32_bf16 v[4:7], v[168:171], v[212:215], v[4:7]
	v_mfma_f32_16x16x32_bf16 v[0:3], v[176:179], v[212:215], v[0:3]
	s_setprio 0
	s_barrier
	s_add_u32 s36, s36, 0x100
	s_addc_u32 s37, s37, 0
	s_add_u32 s43, s43, 0x100
	s_addc_u32 s56, s56, 0
	s_cmp_ge_i32 s46, s19
	s_mov_b32 s40, s46
	s_cbranch_scc0 .LBB0_890
	s_and_b64 vcc, exec, s[10:11]
	s_cbranch_vccz .LBB0_893
	s_barrier

.LBB0_1132:
	v_readlane_b32 s4, v254, 52
	v_readlane_b32 s60, v253, 54
	s_mov_b32 s6, s4
	s_mul_i32 s4, s4, 0x10800
	v_readlane_b32 s68, v253, 62
	v_readlane_b32 s69, v253, 63
	s_add_u32 s20, s68, s4
	v_readlane_b32 s70, v254, 0
	s_addc_u32 s21, s69, 0
	s_mul_i32 s4, s6, 0x5800
	v_readlane_b32 s71, v254, 1
	s_add_u32 s22, s70, s4
	s_addc_u32 s23, s71, 0
	s_add_u32 s54, s16, 0x24f00000
	v_readlane_b32 s62, v253, 56
	s_addc_u32 s55, s17, 0
	v_readlane_b32 s63, v253, 57
	s_add_u32 s62, s16, 0x4bf00000
	s_addc_u32 s63, s17, 0
	s_add_u32 s31, s16, 0x4c800000
	s_addc_u32 s90, s17, 0
	s_lshl_b32 s70, s0, 6
	s_lshl_b32 s6, s0, 13
	s_lshl_b32 s0, s1, 5
	s_and_b32 s36, s0, 0x60
	s_add_i32 m0, s88, 0x18000
	v_lshl_add_u64 v[6:7], v[6:7], 0, s[82:83]
	s_lshl_b32 s7, s36, 7
	s_waitcnt vmcnt(2)
	s_barrier
	global_load_lds_dwordx4 v[6:7], off
	v_lshl_add_u64 v[4:5], v[4:5], 0, s[82:83]
	s_add_i32 m0, s88, 0x1a000
	s_add_i32 s1, s88, 0x8000
	s_add_i32 s0, s88, 0xa000
	v_readlane_b32 s5, v254, 53
	global_load_lds_dwordx4 v[4:5], off
	v_lshl_add_u64 v[0:1], v[0:1], 0, s[82:83]
	s_mov_b32 m0, s1
	s_add_u32 s4, s42, 0x80080
	global_load_lds_dwordx4 v[0:1], off
	v_lshl_add_u64 v[0:1], v[2:3], 0, s[82:83]
	s_mov_b32 m0, s0
	s_addc_u32 s5, s43, 0
	global_load_lds_dwordx4 v[0:1], off
	s_add_i32 m0, s88, 0x1c000
	s_nop 0
	global_load_lds_dwordx4 v96, s[4:5]
	s_add_i32 m0, s88, 0x1e000
	v_readlane_b32 s64, v253, 58
	global_load_lds_dwordx4 v166, s[4:5]
	v_lshrrev_b32_e32 v0, 1, v8
	v_readlane_b32 s65, v253, 59
	v_and_b32_e32 v2, 24, v0
	s_cmpk_lt_u32 s8, 0x100
	v_and_b32_e32 v192, 15, v8
	v_lshlrev_b32_e32 v0, 1, v2
	v_lshlrev_b32_e32 v3, 2, v8
	s_cselect_b64 s[56:57], -1, 0
	s_bfe_i64 s[64:65], s[92:93], 0x200000
	s_lshl_b32 s37, s36, 1
	v_lshl_or_b32 v1, v192, 6, v0
	v_and_b32_e32 v3, 32, v3
	s_add_u32 s16, s16, s37
	v_bitop3_b32 v4, v1, s6, v3 bitop3:0xde
	v_bitop3_b32 v204, v1, s7, v3 bitop3:0xde
	s_addc_u32 s17, s17, 0
	v_mov_b32_e32 v1, v97
	v_lshl_add_u64 v[0:1], s[16:17], 0, v[0:1]
	s_mov_b64 s[16:17], 0x3cf00000
	v_lshl_add_u64 v[168:169], v[0:1], 0, s[16:17]
	v_lshlrev_b32_e32 v0, 15, v9
	v_and_b32_e32 v0, 0xffff0000, v0
	v_lshl_add_u32 v0, v10, 12, v0
	v_and_b32_e32 v1, 1, v9
	v_lshl_or_b32 v0, v1, 6, v0
	v_lshl_add_u32 v170, v11, 1, v0
	v_lshlrev_b32_e32 v0, 15, v12
	v_and_b32_e32 v0, 0xffff0000, v0
	v_readlane_b32 s72, v254, 2
	v_readlane_b32 s73, v254, 3
	s_waitcnt vmcnt(6)
	v_lshl_add_u32 v0, v13, 12, v0
	v_and_b32_e32 v1, 1, v12
	v_readlane_b32 s61, v253, 55
	v_readlane_b32 s74, v254, 4
	v_readlane_b32 s75, v254, 5
	v_lshl_or_b32 v0, v1, 6, v0
	v_readlane_b32 s72, v254, 60
	v_readlane_b32 s66, v253, 60
	v_or_b32_e32 v193, s70, v192
	s_mov_b32 s95, 0
	v_cmp_eq_u32_e64 s[4:5], 0, v192
	v_cmp_ne_u32_e64 s[6:7], 0, v192
	v_cmp_eq_u32_e64 s[8:9], 15, v192
	v_cmp_ne_u32_e64 s[10:11], 15, v192
	v_cmp_gt_u32_e64 s[12:13], 2, v192
	v_cmp_lt_u32_e64 s[14:15], 13, v192
	v_add_u32_e32 v205, -12, v192
	v_or_b32_e32 v206, s36, v2
	v_mov_b32_e32 v171, v97
	v_lshl_add_u32 v172, v14, 1, v0
	v_mov_b32_e32 v173, v97
	v_add_u32_e32 v207, 0, v4
	s_mov_b64 s[52:53], s[42:43]
	s_mov_b64 s[80:81], s[40:41]
	v_readlane_b32 s73, v254, 61
	v_readlane_b32 s71, v254, 62
	s_mov_b32 s74, 0x14080
	s_mov_b32 s75, 0x28000
	s_mov_b32 s60, 0x78000
	s_movk_i32 s61, 0x1000
	s_movk_i32 s68, 0x4000
	s_movk_i32 s69, 0x2000
	v_readlane_b32 s67, v253, 61
	s_barrier
	s_branch .LBB0_1135

.LBB0_1145:
	s_add_i32 s46, s44, 2
	s_add_u32 s42, s40, 0xfff80080
	s_addc_u32 s43, s41, -1
	s_add_i32 s47, 0, 0x10000
	s_cmp_eq_u32 s67, s44
	s_cselect_b32 s45, s81, s43
	s_cselect_b32 s44, s80, s42
	s_cselect_b32 s43, s53, vcc_lo
	s_cselect_b32 s42, s52, s92
	s_add_i32 vcc_hi, 0, 0x14000
	v_add_u32_e32 v110, s47, v204
	v_add_u32_e32 v126, vcc_hi, v204
	ds_read_b128 v[80:83], v110
	ds_read_b128 v[102:105], v110 offset:1024
	ds_read_b128 v[106:109], v110 offset:2048
	ds_read_b128 v[110:113], v110 offset:3072
	ds_read_b128 v[114:117], v126
	ds_read_b128 v[118:121], v126 offset:1024
	ds_read_b128 v[122:125], v126 offset:2048
	ds_read_b128 v[126:129], v126 offset:3072
	s_add_i32 m0, s88, 0xc000
	ds_read_b128 v[174:177], v207
	ds_read_b128 v[178:181], v207 offset:1024
	ds_read_b128 v[182:185], v207 offset:2048
	ds_read_b128 v[186:189], v207 offset:3072
	ds_read_b128 v[196:199], v207 offset:4096
	ds_read_b128 v[200:203], v207 offset:5120
	ds_read_b128 v[208:211], v207 offset:6144
	ds_read_b128 v[212:215], v207 offset:7168
	global_load_lds_dwordx4 v170, s[40:41]
	s_add_i32 m0, s88, 0xe000
	s_nop 0
	global_load_lds_dwordx4 v172, s[40:41]
	s_waitcnt vmcnt(8) lgkmcnt(0)
	s_barrier
	s_setprio 1
	v_mfma_f32_16x16x32_bf16 v[98:101], v[80:83], v[174:177], v[98:101]
	v_mfma_f32_16x16x32_bf16 v[88:91], v[106:109], v[174:177], v[88:91]
	v_mfma_f32_16x16x32_bf16 v[158:161], v[80:83], v[182:185], v[158:161]
	v_mfma_f32_16x16x32_bf16 v[154:157], v[106:109], v[182:185], v[154:157]
	v_mfma_f32_16x16x32_bf16 v[146:149], v[80:83], v[196:199], v[146:149]
	v_mfma_f32_16x16x32_bf16 v[138:141], v[106:109], v[196:199], v[138:141]
	v_mfma_f32_16x16x32_bf16 v[76:79], v[80:83], v[208:211], v[76:79]
	v_mfma_f32_16x16x32_bf16 v[68:71], v[106:109], v[208:211], v[68:71]
	v_mfma_f32_16x16x32_bf16 v[98:101], v[102:105], v[178:181], v[98:101]
	v_mfma_f32_16x16x32_bf16 v[88:91], v[110:113], v[178:181], v[88:91]
	v_mfma_f32_16x16x32_bf16 v[158:161], v[102:105], v[186:189], v[158:161]
	v_mfma_f32_16x16x32_bf16 v[154:157], v[110:113], v[186:189], v[154:157]
	v_mfma_f32_16x16x32_bf16 v[146:149], v[102:105], v[200:203], v[146:149]
	v_mfma_f32_16x16x32_bf16 v[138:141], v[110:113], v[200:203], v[138:141]
	v_mfma_f32_16x16x32_bf16 v[76:79], v[102:105], v[212:215], v[76:79]
	v_mfma_f32_16x16x32_bf16 v[68:71], v[110:113], v[212:215], v[68:71]
	v_mfma_f32_16x16x32_bf16 v[92:95], v[114:117], v[174:177], v[92:95]
	v_mfma_f32_16x16x32_bf16 v[84:87], v[122:125], v[174:177], v[84:87]
	v_mfma_f32_16x16x32_bf16 v[150:153], v[114:117], v[182:185], v[150:153]
	v_mfma_f32_16x16x32_bf16 v[142:145], v[122:125], v[182:185], v[142:145]
	v_mfma_f32_16x16x32_bf16 v[134:137], v[114:117], v[196:199], v[134:137]
	v_mfma_f32_16x16x32_bf16 v[130:133], v[122:125], v[196:199], v[130:133]
	v_mfma_f32_16x16x32_bf16 v[72:75], v[114:117], v[208:211], v[72:75]
	v_mfma_f32_16x16x32_bf16 v[64:67], v[122:125], v[208:211], v[64:67]
	v_mfma_f32_16x16x32_bf16 v[92:95], v[118:121], v[178:181], v[92:95]
	v_mfma_f32_16x16x32_bf16 v[84:87], v[126:129], v[178:181], v[84:87]
	v_mfma_f32_16x16x32_bf16 v[150:153], v[118:121], v[186:189], v[150:153]
	v_mfma_f32_16x16x32_bf16 v[142:145], v[126:129], v[186:189], v[142:145]
	v_mfma_f32_16x16x32_bf16 v[134:137], v[118:121], v[200:203], v[134:137]
	v_mfma_f32_16x16x32_bf16 v[130:133], v[126:129], v[200:203], v[130:133]
	v_mfma_f32_16x16x32_bf16 v[72:75], v[118:121], v[212:215], v[72:75]
	v_mfma_f32_16x16x32_bf16 v[64:67], v[126:129], v[212:215], v[64:67]
	s_setprio 0
	s_barrier
	s_add_i32 s47, s47, s59
	v_lshl_add_u64 v[190:191], s[42:43], 0, v[96:97]
	s_mov_b32 m0, s47
	ds_read_b128 v[174:177], v207 offset:16384
	ds_read_b128 v[178:181], v207 offset:17408
	ds_read_b128 v[182:185], v207 offset:18432
	ds_read_b128 v[186:189], v207 offset:19456
	ds_read_b128 v[196:199], v207 offset:20480
	ds_read_b128 v[200:203], v207 offset:21504
	ds_read_b128 v[208:211], v207 offset:22528
	ds_read_b128 v[212:215], v207 offset:23552
	global_load_lds_dwordx4 v[190:191], off
	s_add_i32 m0, s47, 0x2000
	s_add_u32 s50, s42, 0x80000
	v_lshl_add_u64 v[216:217], s[42:43], 0, v[166:167]
	s_addc_u32 s51, s43, 0
	s_add_i32 s47, vcc_hi, s59
	global_load_lds_dwordx4 v[216:217], off
	s_mov_b32 m0, s47
	v_lshl_add_u64 v[220:221], s[44:45], 0, v[164:165]
	global_load_lds_dwordx4 v96, s[50:51]
	s_add_i32 m0, s47, 0x2000
	s_nop 0
	global_load_lds_dwordx4 v166, s[50:51]
	s_mov_b32 m0, s88
	v_lshl_add_u64 v[218:219], s[44:45], 0, v[162:163]
	global_load_lds_dwordx4 v[218:219], off
	s_mov_b32 m0, s28
	s_nop 0
	global_load_lds_dwordx4 v[220:221], off
	s_waitcnt vmcnt(8) lgkmcnt(0)
	s_barrier
	s_setprio 1
	v_mfma_f32_16x16x32_bf16 v[28:31], v[80:83], v[174:177], v[28:31]
	v_mfma_f32_16x16x32_bf16 v[20:23], v[106:109], v[174:177], v[20:23]
	v_mfma_f32_16x16x32_bf16 v[60:63], v[80:83], v[182:185], v[60:63]
	v_mfma_f32_16x16x32_bf16 v[56:59], v[106:109], v[182:185], v[56:59]
	v_mfma_f32_16x16x32_bf16 v[48:51], v[80:83], v[196:199], v[48:51]
	v_mfma_f32_16x16x32_bf16 v[40:43], v[106:109], v[196:199], v[40:43]
	v_mfma_f32_16x16x32_bf16 v[12:15], v[80:83], v[208:211], v[12:15]
	v_mfma_f32_16x16x32_bf16 v[4:7], v[106:109], v[208:211], v[4:7]
	v_mfma_f32_16x16x32_bf16 v[28:31], v[102:105], v[178:181], v[28:31]
	v_mfma_f32_16x16x32_bf16 v[20:23], v[110:113], v[178:181], v[20:23]
	v_mfma_f32_16x16x32_bf16 v[60:63], v[102:105], v[186:189], v[60:63]
	v_mfma_f32_16x16x32_bf16 v[56:59], v[110:113], v[186:189], v[56:59]
	v_mfma_f32_16x16x32_bf16 v[48:51], v[102:105], v[200:203], v[48:51]
	v_mfma_f32_16x16x32_bf16 v[40:43], v[110:113], v[200:203], v[40:43]
	v_mfma_f32_16x16x32_bf16 v[12:15], v[102:105], v[212:215], v[12:15]
	v_mfma_f32_16x16x32_bf16 v[4:7], v[110:113], v[212:215], v[4:7]
	v_mfma_f32_16x16x32_bf16 v[24:27], v[114:117], v[174:177], v[24:27]
	v_mfma_f32_16x16x32_bf16 v[16:19], v[122:125], v[174:177], v[16:19]
	v_mfma_f32_16x16x32_bf16 v[52:55], v[114:117], v[182:185], v[52:55]
	v_mfma_f32_16x16x32_bf16 v[44:47], v[122:125], v[182:185], v[44:47]
	v_mfma_f32_16x16x32_bf16 v[36:39], v[114:117], v[196:199], v[36:39]
	v_mfma_f32_16x16x32_bf16 v[32:35], v[122:125], v[196:199], v[32:35]
	v_mfma_f32_16x16x32_bf16 v[8:11], v[114:117], v[208:211], v[8:11]
	v_mfma_f32_16x16x32_bf16 v[0:3], v[122:125], v[208:211], v[0:3]
	v_mfma_f32_16x16x32_bf16 v[24:27], v[118:121], v[178:181], v[24:27]
	v_mfma_f32_16x16x32_bf16 v[16:19], v[126:129], v[178:181], v[16:19]
	v_mfma_f32_16x16x32_bf16 v[52:55], v[118:121], v[186:189], v[52:55]
	v_mfma_f32_16x16x32_bf16 v[44:47], v[126:129], v[186:189], v[44:47]
	v_mfma_f32_16x16x32_bf16 v[36:39], v[118:121], v[200:203], v[36:39]
	v_mfma_f32_16x16x32_bf16 v[32:35], v[126:129], v[200:203], v[32:35]
	v_mfma_f32_16x16x32_bf16 v[8:11], v[118:121], v[212:215], v[8:11]
	v_mfma_f32_16x16x32_bf16 v[0:3], v[126:129], v[212:215], v[0:3]
	s_setprio 0
	s_barrier
	s_add_i32 s47, 0, 0x18000
	s_add_i32 s50, 0, 0x1c000
	v_add_u32_e32 v110, s47, v204
	v_add_u32_e32 v126, s50, v204
	ds_read_b128 v[80:83], v110
	ds_read_b128 v[102:105], v110 offset:1024
	ds_read_b128 v[106:109], v110 offset:2048
	ds_read_b128 v[110:113], v110 offset:3072
	ds_read_b128 v[114:117], v126
	ds_read_b128 v[118:121], v126 offset:1024
	ds_read_b128 v[122:125], v126 offset:2048
	ds_read_b128 v[126:129], v126 offset:3072
	s_add_u32 s44, s44, 0x80000
	s_addc_u32 s45, s45, 0
	s_mov_b32 m0, s29
	ds_read_b128 v[174:177], v207 offset:32768
	ds_read_b128 v[178:181], v207 offset:33792
	ds_read_b128 v[182:185], v207 offset:34816
	ds_read_b128 v[186:189], v207 offset:35840
	ds_read_b128 v[196:199], v207 offset:36864
	ds_read_b128 v[200:203], v207 offset:37888
	ds_read_b128 v[208:211], v207 offset:38912
	ds_read_b128 v[212:215], v207 offset:39936
	global_load_lds_dwordx4 v162, s[44:45]
	s_mov_b32 m0, s30
	s_nop 0
	global_load_lds_dwordx4 v164, s[44:45]
	s_waitcnt vmcnt(8) lgkmcnt(0)
	s_barrier
	s_setprio 1
	v_mfma_f32_16x16x32_bf16 v[98:101], v[80:83], v[174:177], v[98:101]
	v_mfma_f32_16x16x32_bf16 v[88:91], v[106:109], v[174:177], v[88:91]
	v_mfma_f32_16x16x32_bf16 v[158:161], v[80:83], v[182:185], v[158:161]
	v_mfma_f32_16x16x32_bf16 v[154:157], v[106:109], v[182:185], v[154:157]
	v_mfma_f32_16x16x32_bf16 v[146:149], v[80:83], v[196:199], v[146:149]
	v_mfma_f32_16x16x32_bf16 v[138:141], v[106:109], v[196:199], v[138:141]
	v_mfma_f32_16x16x32_bf16 v[76:79], v[80:83], v[208:211], v[76:79]
	v_mfma_f32_16x16x32_bf16 v[68:71], v[106:109], v[208:211], v[68:71]
	v_mfma_f32_16x16x32_bf16 v[98:101], v[102:105], v[178:181], v[98:101]
	v_mfma_f32_16x16x32_bf16 v[88:91], v[110:113], v[178:181], v[88:91]
	v_mfma_f32_16x16x32_bf16 v[158:161], v[102:105], v[186:189], v[158:161]
	v_mfma_f32_16x16x32_bf16 v[154:157], v[110:113], v[186:189], v[154:157]
	v_mfma_f32_16x16x32_bf16 v[146:149], v[102:105], v[200:203], v[146:149]
	v_mfma_f32_16x16x32_bf16 v[138:141], v[110:113], v[200:203], v[138:141]
	v_mfma_f32_16x16x32_bf16 v[76:79], v[102:105], v[212:215], v[76:79]
	v_mfma_f32_16x16x32_bf16 v[68:71], v[110:113], v[212:215], v[68:71]
	v_mfma_f32_16x16x32_bf16 v[92:95], v[114:117], v[174:177], v[92:95]
	v_mfma_f32_16x16x32_bf16 v[84:87], v[122:125], v[174:177], v[84:87]
	v_mfma_f32_16x16x32_bf16 v[150:153], v[114:117], v[182:185], v[150:153]
	v_mfma_f32_16x16x32_bf16 v[142:145], v[122:125], v[182:185], v[142:145]
	v_mfma_f32_16x16x32_bf16 v[134:137], v[114:117], v[196:199], v[134:137]
	v_mfma_f32_16x16x32_bf16 v[130:133], v[122:125], v[196:199], v[130:133]
	v_mfma_f32_16x16x32_bf16 v[72:75], v[114:117], v[208:211], v[72:75]
	v_mfma_f32_16x16x32_bf16 v[64:67], v[122:125], v[208:211], v[64:67]
	v_mfma_f32_16x16x32_bf16 v[92:95], v[118:121], v[178:181], v[92:95]
	v_mfma_f32_16x16x32_bf16 v[84:87], v[126:129], v[178:181], v[84:87]
	v_mfma_f32_16x16x32_bf16 v[150:153], v[118:121], v[186:189], v[150:153]
	v_mfma_f32_16x16x32_bf16 v[142:145], v[126:129], v[186:189], v[142:145]
	v_mfma_f32_16x16x32_bf16 v[134:137], v[118:121], v[200:203], v[134:137]
	v_mfma_f32_16x16x32_bf16 v[130:133], v[126:129], v[200:203], v[130:133]
	v_mfma_f32_16x16x32_bf16 v[72:75], v[118:121], v[212:215], v[72:75]
	v_mfma_f32_16x16x32_bf16 v[64:67], v[126:129], v[212:215], v[64:67]
	s_setprio 0
	s_barrier
	s_add_i32 s44, s47, s59
	v_lshl_add_u64 v[190:191], v[190:191], 0, s[82:83]
	s_mov_b32 m0, s44
	ds_read_b128 v[174:177], v207 offset:49152
	ds_read_b128 v[178:181], v207 offset:50176
	ds_read_b128 v[182:185], v207 offset:51200
	ds_read_b128 v[186:189], v207 offset:52224
	ds_read_b128 v[196:199], v207 offset:53248
	ds_read_b128 v[200:203], v207 offset:54272
	ds_read_b128 v[208:211], v207 offset:55296
	ds_read_b128 v[212:215], v207 offset:56320
	global_load_lds_dwordx4 v[190:191], off
	s_add_i32 m0, s44, 0x2000
	s_add_u32 s42, s42, 0x80080
	v_lshl_add_u64 v[190:191], v[216:217], 0, s[82:83]
	s_addc_u32 s43, s43, 0
	s_add_i32 s44, s50, s59
	global_load_lds_dwordx4 v[190:191], off
	s_mov_b32 m0, s44
	s_nop 0
	global_load_lds_dwordx4 v96, s[42:43]
	s_add_i32 m0, s44, 0x2000
	s_nop 0
	global_load_lds_dwordx4 v166, s[42:43]
	s_mov_b32 m0, s1
	v_lshl_add_u64 v[190:191], v[218:219], 0, s[82:83]
	global_load_lds_dwordx4 v[190:191], off
	s_mov_b32 m0, s0
	v_lshl_add_u64 v[190:191], v[220:221], 0, s[82:83]
	global_load_lds_dwordx4 v[190:191], off
	s_waitcnt vmcnt(8) lgkmcnt(0)
	s_barrier
	s_setprio 1
	v_mfma_f32_16x16x32_bf16 v[28:31], v[80:83], v[174:177], v[28:31]
	v_mfma_f32_16x16x32_bf16 v[20:23], v[106:109], v[174:177], v[20:23]
	v_mfma_f32_16x16x32_bf16 v[60:63], v[80:83], v[182:185], v[60:63]
	v_mfma_f32_16x16x32_bf16 v[56:59], v[106:109], v[182:185], v[56:59]
	v_mfma_f32_16x16x32_bf16 v[48:51], v[80:83], v[196:199], v[48:51]
	v_mfma_f32_16x16x32_bf16 v[40:43], v[106:109], v[196:199], v[40:43]
	v_mfma_f32_16x16x32_bf16 v[12:15], v[80:83], v[208:211], v[12:15]
	v_mfma_f32_16x16x32_bf16 v[4:7], v[106:109], v[208:211], v[4:7]
	v_mfma_f32_16x16x32_bf16 v[28:31], v[102:105], v[178:181], v[28:31]
	v_mfma_f32_16x16x32_bf16 v[20:23], v[110:113], v[178:181], v[20:23]
	v_mfma_f32_16x16x32_bf16 v[60:63], v[102:105], v[186:189], v[60:63]
	v_mfma_f32_16x16x32_bf16 v[56:59], v[110:113], v[186:189], v[56:59]
	v_mfma_f32_16x16x32_bf16 v[48:51], v[102:105], v[200:203], v[48:51]
	v_mfma_f32_16x16x32_bf16 v[40:43], v[110:113], v[200:203], v[40:43]
	v_mfma_f32_16x16x32_bf16 v[12:15], v[102:105], v[212:215], v[12:15]
	v_mfma_f32_16x16x32_bf16 v[4:7], v[110:113], v[212:215], v[4:7]
	v_mfma_f32_16x16x32_bf16 v[24:27], v[114:117], v[174:177], v[24:27]
	v_mfma_f32_16x16x32_bf16 v[16:19], v[122:125], v[174:177], v[16:19]
	v_mfma_f32_16x16x32_bf16 v[52:55], v[114:117], v[182:185], v[52:55]
	v_mfma_f32_16x16x32_bf16 v[44:47], v[122:125], v[182:185], v[44:47]
	v_mfma_f32_16x16x32_bf16 v[36:39], v[114:117], v[196:199], v[36:39]
	v_mfma_f32_16x16x32_bf16 v[32:35], v[122:125], v[196:199], v[32:35]
	v_mfma_f32_16x16x32_bf16 v[8:11], v[114:117], v[208:211], v[8:11]
	v_mfma_f32_16x16x32_bf16 v[0:3], v[122:125], v[208:211], v[0:3]
	v_mfma_f32_16x16x32_bf16 v[24:27], v[118:121], v[178:181], v[24:27]
	v_mfma_f32_16x16x32_bf16 v[16:19], v[126:129], v[178:181], v[16:19]
	v_mfma_f32_16x16x32_bf16 v[52:55], v[118:121], v[186:189], v[52:55]
	v_mfma_f32_16x16x32_bf16 v[44:47], v[126:129], v[186:189], v[44:47]
	v_mfma_f32_16x16x32_bf16 v[36:39], v[118:121], v[200:203], v[36:39]
	v_mfma_f32_16x16x32_bf16 v[32:35], v[126:129], v[200:203], v[32:35]
	v_mfma_f32_16x16x32_bf16 v[8:11], v[118:121], v[212:215], v[8:11]
	v_mfma_f32_16x16x32_bf16 v[0:3], v[126:129], v[212:215], v[0:3]
	s_setprio 0
	s_barrier
	s_add_u32 s40, s40, 0x100
	s_addc_u32 s41, s41, 0
	s_add_u32 s92, s92, 0x100
	s_addc_u32 vcc_lo, vcc_lo, 0
	s_cmp_ge_i32 s46, s49
	s_mov_b32 s44, s46
	s_cbranch_scc0 .LBB0_1145
	s_and_b64 vcc, exec, s[56:57]
	s_cbranch_vccz .LBB0_1148
	s_barrier

.LBB0_1336:
	s_lshl_b32 s4, s11, 5
	s_and_b32 s14, s4, 0x60
	s_add_i32 m0, s36, 0x18000
	v_lshl_add_u64 v[6:7], v[6:7], 0, s[82:83]
	s_lshl_b32 s13, s10, 13
	s_lshl_b32 s11, s14, 7
	s_waitcnt vmcnt(2)
	s_barrier
	global_load_lds_dwordx4 v[6:7], off
	v_lshl_add_u64 v[4:5], v[4:5], 0, s[82:83]
	s_add_i32 m0, s36, 0x1a000
	s_add_i32 s40, s36, 0x8000
	s_add_i32 s41, s36, 0xa000
	global_load_lds_dwordx4 v[4:5], off
	v_lshl_add_u64 v[0:1], v[0:1], 0, s[82:83]
	s_mov_b32 m0, s40
	s_add_u32 s4, s18, 0x160080
	global_load_lds_dwordx4 v[0:1], off
	v_lshl_add_u64 v[0:1], v[2:3], 0, s[82:83]
	s_mov_b32 m0, s41
	s_addc_u32 s5, s19, 0
	global_load_lds_dwordx4 v[0:1], off
	s_add_i32 m0, s36, 0x1c000
	s_nop 0
	global_load_lds_dwordx4 v132, s[4:5]
	s_add_i32 m0, s36, 0x1e000
	s_cmpk_lt_u32 s12, 0x100
	global_load_lds_dwordx4 v136, s[4:5]
	v_lshrrev_b32_e32 v0, 1, v8
	v_and_b32_e32 v0, 24, v0
	v_and_b32_e32 v1, 15, v8
	v_lshlrev_b32_e32 v2, 1, v0
	v_lshl_or_b32 v144, s10, 6, v1
	v_lshl_or_b32 v1, v1, 6, v2
	v_lshlrev_b32_e32 v2, 2, v8
	v_and_b32_e32 v2, 32, v2
	s_movk_i32 s12, 0x1600
	v_bitop3_b32 v4, v1, s13, v2 bitop3:0xde
	v_bitop3_b32 v145, v1, s11, v2 bitop3:0xde
	v_lshrrev_b32_e32 v1, 1, v9
	v_mul_lo_u32 v2, v11, s12
	s_mov_b32 s2, 0x16000
	v_mad_u64_u32 v[2:3], s[4:5], v1, s2, v[2:3]
	v_or_b32_e32 v1, v2, v10
	v_add_lshl_u32 v96, v1, v12, 1
	v_lshrrev_b32_e32 v1, 1, v13
	v_mul_lo_u32 v2, v15, s12
	v_mad_u64_u32 v[2:3], s[4:5], v1, s2, v[2:3]
	s_waitcnt vmcnt(6)
	s_mov_b64 s[20:21], 0x160080
	v_or_b32_e32 v1, v2, v14
	v_lshl_add_u64 v[138:139], v[96:97], 0, s[20:21]
	v_add_lshl_u32 v96, v1, v16, 1
	s_cselect_b64 s[10:11], -1, 0
	s_ashr_i32 s42, s0, 31
	v_lshl_add_u64 v[140:141], v[96:97], 0, s[20:21]
	s_mov_b32 s43, 0
	v_add_u32_e32 v146, 0, v4
	s_lshl_b32 s92, s14, 1
	v_lshlrev_b32_e32 v96, 1, v0
	s_mov_b64 s[14:15], s[18:19]
	s_mov_b64 s[12:13], s[16:17]
	s_barrier
	s_branch .LBB0_1339

.LBB0_1349:
	s_add_i32 s46, s20, 2
	s_add_u32 s18, s16, 0x100
	s_addc_u32 s19, s17, 0
	s_add_i32 s47, 0, 0x10000
	s_cmp_eq_u32 s56, s20
	s_cselect_b32 s23, s13, s19
	s_cselect_b32 s22, s12, s18
	v_add_u32_e32 v142, s47, v145
	s_cselect_b32 s21, s15, s58
	s_cselect_b32 s20, s14, s57
	s_add_i32 s50, 0, 0x14000
	ds_read_b128 v[148:151], v142
	ds_read_b128 v[152:155], v142 offset:1024
	ds_read_b128 v[156:159], v142 offset:2048
	ds_read_b128 v[160:163], v142 offset:3072
	v_add_u32_e32 v142, s50, v145
	ds_read_b128 v[164:167], v142
	ds_read_b128 v[168:171], v142 offset:1024
	ds_read_b128 v[172:175], v142 offset:2048
	ds_read_b128 v[176:179], v142 offset:3072
	v_lshl_add_u64 v[142:143], s[16:17], 0, v[138:139]
	s_add_i32 m0, s36, 0xc000
	ds_read_b128 v[180:183], v146
	ds_read_b128 v[184:187], v146 offset:1024
	ds_read_b128 v[188:191], v146 offset:2048
	ds_read_b128 v[196:199], v146 offset:3072
	ds_read_b128 v[200:203], v146 offset:4096
	ds_read_b128 v[204:207], v146 offset:5120
	ds_read_b128 v[208:211], v146 offset:6144
	ds_read_b128 v[212:215], v146 offset:7168
	global_load_lds_dwordx4 v[142:143], off
	s_add_i32 m0, s36, 0xe000
	v_lshl_add_u64 v[142:143], s[16:17], 0, v[140:141]
	global_load_lds_dwordx4 v[142:143], off
	s_waitcnt vmcnt(8) lgkmcnt(0)
	s_barrier
	s_setprio 1
	v_mfma_f32_16x16x32_bf16 v[126:129], v[148:151], v[180:183], v[126:129]
	v_mfma_f32_16x16x32_bf16 v[122:125], v[156:159], v[180:183], v[122:125]
	v_mfma_f32_16x16x32_bf16 v[118:121], v[148:151], v[188:191], v[118:121]
	v_mfma_f32_16x16x32_bf16 v[110:113], v[156:159], v[188:191], v[110:113]
	v_mfma_f32_16x16x32_bf16 v[102:105], v[148:151], v[200:203], v[102:105]
	v_mfma_f32_16x16x32_bf16 v[92:95], v[156:159], v[200:203], v[92:95]
	v_mfma_f32_16x16x32_bf16 v[84:87], v[148:151], v[208:211], v[84:87]
	v_mfma_f32_16x16x32_bf16 v[76:79], v[156:159], v[208:211], v[76:79]
	v_mfma_f32_16x16x32_bf16 v[126:129], v[152:155], v[184:187], v[126:129]
	v_mfma_f32_16x16x32_bf16 v[122:125], v[160:163], v[184:187], v[122:125]
	v_mfma_f32_16x16x32_bf16 v[118:121], v[152:155], v[196:199], v[118:121]
	v_mfma_f32_16x16x32_bf16 v[110:113], v[160:163], v[196:199], v[110:113]
	v_mfma_f32_16x16x32_bf16 v[102:105], v[152:155], v[204:207], v[102:105]
	v_mfma_f32_16x16x32_bf16 v[92:95], v[160:163], v[204:207], v[92:95]
	v_mfma_f32_16x16x32_bf16 v[84:87], v[152:155], v[212:215], v[84:87]
	v_mfma_f32_16x16x32_bf16 v[76:79], v[160:163], v[212:215], v[76:79]
	v_mfma_f32_16x16x32_bf16 v[114:117], v[164:167], v[180:183], v[114:117]
	v_mfma_f32_16x16x32_bf16 v[106:109], v[172:175], v[180:183], v[106:109]
	v_mfma_f32_16x16x32_bf16 v[98:101], v[164:167], v[188:191], v[98:101]
	v_mfma_f32_16x16x32_bf16 v[88:91], v[172:175], v[188:191], v[88:91]
	v_mfma_f32_16x16x32_bf16 v[80:83], v[164:167], v[200:203], v[80:83]
	v_mfma_f32_16x16x32_bf16 v[72:75], v[172:175], v[200:203], v[72:75]
	v_mfma_f32_16x16x32_bf16 v[68:71], v[164:167], v[208:211], v[68:71]
	v_mfma_f32_16x16x32_bf16 v[64:67], v[172:175], v[208:211], v[64:67]
	v_mfma_f32_16x16x32_bf16 v[114:117], v[168:171], v[184:187], v[114:117]
	v_mfma_f32_16x16x32_bf16 v[106:109], v[176:179], v[184:187], v[106:109]
	v_mfma_f32_16x16x32_bf16 v[98:101], v[168:171], v[196:199], v[98:101]
	v_mfma_f32_16x16x32_bf16 v[88:91], v[176:179], v[196:199], v[88:91]
	v_mfma_f32_16x16x32_bf16 v[80:83], v[168:171], v[204:207], v[80:83]
	v_mfma_f32_16x16x32_bf16 v[72:75], v[176:179], v[204:207], v[72:75]
	v_mfma_f32_16x16x32_bf16 v[68:71], v[168:171], v[212:215], v[68:71]
	v_mfma_f32_16x16x32_bf16 v[64:67], v[176:179], v[212:215], v[64:67]
	s_setprio 0
	s_barrier
	s_add_i32 s16, s47, s31
	v_lshl_add_u64 v[142:143], s[20:21], 0, v[132:133]
	s_mov_b32 m0, s16
	ds_read_b128 v[180:183], v146 offset:16384
	ds_read_b128 v[184:187], v146 offset:17408
	ds_read_b128 v[188:191], v146 offset:18432
	ds_read_b128 v[196:199], v146 offset:19456
	ds_read_b128 v[200:203], v146 offset:20480
	ds_read_b128 v[204:207], v146 offset:21504
	ds_read_b128 v[208:211], v146 offset:22528
	ds_read_b128 v[212:215], v146 offset:23552
	global_load_lds_dwordx4 v[142:143], off
	s_add_i32 m0, s16, 0x2000
	s_add_u32 s16, s20, 0x160000
	v_lshl_add_u64 v[192:193], s[20:21], 0, v[136:137]
	s_addc_u32 s17, s21, 0
	s_add_i32 s47, s50, s31
	global_load_lds_dwordx4 v[192:193], off
	s_mov_b32 m0, s47
	v_lshl_add_u64 v[218:219], s[22:23], 0, v[134:135]
	global_load_lds_dwordx4 v132, s[16:17]
	s_add_i32 m0, s47, 0x2000
	s_nop 0
	global_load_lds_dwordx4 v136, s[16:17]
	s_mov_b32 m0, s36
	v_lshl_add_u64 v[216:217], s[22:23], 0, v[130:131]
	global_load_lds_dwordx4 v[216:217], off
	s_mov_b32 m0, s37
	s_nop 0
	global_load_lds_dwordx4 v[218:219], off
	s_waitcnt vmcnt(8) lgkmcnt(0)
	s_barrier
	s_setprio 1
	v_mfma_f32_16x16x32_bf16 v[60:63], v[148:151], v[180:183], v[60:63]
	v_mfma_f32_16x16x32_bf16 v[56:59], v[156:159], v[180:183], v[56:59]
	v_mfma_f32_16x16x32_bf16 v[52:55], v[148:151], v[188:191], v[52:55]
	v_mfma_f32_16x16x32_bf16 v[44:47], v[156:159], v[188:191], v[44:47]
	v_mfma_f32_16x16x32_bf16 v[36:39], v[148:151], v[200:203], v[36:39]
	v_mfma_f32_16x16x32_bf16 v[28:31], v[156:159], v[200:203], v[28:31]
	v_mfma_f32_16x16x32_bf16 v[20:23], v[148:151], v[208:211], v[20:23]
	v_mfma_f32_16x16x32_bf16 v[12:15], v[156:159], v[208:211], v[12:15]
	v_mfma_f32_16x16x32_bf16 v[60:63], v[152:155], v[184:187], v[60:63]
	v_mfma_f32_16x16x32_bf16 v[56:59], v[160:163], v[184:187], v[56:59]
	v_mfma_f32_16x16x32_bf16 v[52:55], v[152:155], v[196:199], v[52:55]
	v_mfma_f32_16x16x32_bf16 v[44:47], v[160:163], v[196:199], v[44:47]
	v_mfma_f32_16x16x32_bf16 v[36:39], v[152:155], v[204:207], v[36:39]
	v_mfma_f32_16x16x32_bf16 v[28:31], v[160:163], v[204:207], v[28:31]
	v_mfma_f32_16x16x32_bf16 v[20:23], v[152:155], v[212:215], v[20:23]
	v_mfma_f32_16x16x32_bf16 v[12:15], v[160:163], v[212:215], v[12:15]
	v_mfma_f32_16x16x32_bf16 v[48:51], v[164:167], v[180:183], v[48:51]
	v_mfma_f32_16x16x32_bf16 v[40:43], v[172:175], v[180:183], v[40:43]
	v_mfma_f32_16x16x32_bf16 v[32:35], v[164:167], v[188:191], v[32:35]
	v_mfma_f32_16x16x32_bf16 v[24:27], v[172:175], v[188:191], v[24:27]
	v_mfma_f32_16x16x32_bf16 v[16:19], v[164:167], v[200:203], v[16:19]
	v_mfma_f32_16x16x32_bf16 v[8:11], v[172:175], v[200:203], v[8:11]
	v_mfma_f32_16x16x32_bf16 v[4:7], v[164:167], v[208:211], v[4:7]
	v_mfma_f32_16x16x32_bf16 v[0:3], v[172:175], v[208:211], v[0:3]
	v_mfma_f32_16x16x32_bf16 v[48:51], v[168:171], v[184:187], v[48:51]
	v_mfma_f32_16x16x32_bf16 v[40:43], v[176:179], v[184:187], v[40:43]
	v_mfma_f32_16x16x32_bf16 v[32:35], v[168:171], v[196:199], v[32:35]
	v_mfma_f32_16x16x32_bf16 v[24:27], v[176:179], v[196:199], v[24:27]
	v_mfma_f32_16x16x32_bf16 v[16:19], v[168:171], v[204:207], v[16:19]
	v_mfma_f32_16x16x32_bf16 v[8:11], v[176:179], v[204:207], v[8:11]
	v_mfma_f32_16x16x32_bf16 v[4:7], v[168:171], v[212:215], v[4:7]
	v_mfma_f32_16x16x32_bf16 v[0:3], v[176:179], v[212:215], v[0:3]
	s_setprio 0
	s_barrier
	s_add_i32 s47, 0, 0x18000
	v_add_u32_e32 v147, s47, v145
	s_add_i32 s50, 0, 0x1c000
	ds_read_b128 v[148:151], v147
	ds_read_b128 v[152:155], v147 offset:1024
	ds_read_b128 v[156:159], v147 offset:2048
	ds_read_b128 v[160:163], v147 offset:3072
	v_add_u32_e32 v147, s50, v145
	ds_read_b128 v[164:167], v147
	ds_read_b128 v[168:171], v147 offset:1024
	ds_read_b128 v[172:175], v147 offset:2048
	ds_read_b128 v[176:179], v147 offset:3072
	s_add_u32 s16, s22, 0x160000
	s_addc_u32 s17, s23, 0
	s_mov_b32 m0, s38
	ds_read_b128 v[180:183], v146 offset:32768
	ds_read_b128 v[184:187], v146 offset:33792
	ds_read_b128 v[188:191], v146 offset:34816
	ds_read_b128 v[196:199], v146 offset:35840
	ds_read_b128 v[200:203], v146 offset:36864
	ds_read_b128 v[204:207], v146 offset:37888
	ds_read_b128 v[208:211], v146 offset:38912
	ds_read_b128 v[212:215], v146 offset:39936
	global_load_lds_dwordx4 v130, s[16:17]
	s_mov_b32 m0, s39
	s_nop 0
	global_load_lds_dwordx4 v134, s[16:17]
	s_waitcnt vmcnt(8) lgkmcnt(0)
	s_barrier
	s_setprio 1
	v_mfma_f32_16x16x32_bf16 v[126:129], v[148:151], v[180:183], v[126:129]
	v_mfma_f32_16x16x32_bf16 v[122:125], v[156:159], v[180:183], v[122:125]
	v_mfma_f32_16x16x32_bf16 v[118:121], v[148:151], v[188:191], v[118:121]
	v_mfma_f32_16x16x32_bf16 v[110:113], v[156:159], v[188:191], v[110:113]
	v_mfma_f32_16x16x32_bf16 v[102:105], v[148:151], v[200:203], v[102:105]
	v_mfma_f32_16x16x32_bf16 v[92:95], v[156:159], v[200:203], v[92:95]
	v_mfma_f32_16x16x32_bf16 v[84:87], v[148:151], v[208:211], v[84:87]
	v_mfma_f32_16x16x32_bf16 v[76:79], v[156:159], v[208:211], v[76:79]
	v_mfma_f32_16x16x32_bf16 v[126:129], v[152:155], v[184:187], v[126:129]
	v_mfma_f32_16x16x32_bf16 v[122:125], v[160:163], v[184:187], v[122:125]
	v_mfma_f32_16x16x32_bf16 v[118:121], v[152:155], v[196:199], v[118:121]
	v_mfma_f32_16x16x32_bf16 v[110:113], v[160:163], v[196:199], v[110:113]
	v_mfma_f32_16x16x32_bf16 v[102:105], v[152:155], v[204:207], v[102:105]
	v_mfma_f32_16x16x32_bf16 v[92:95], v[160:163], v[204:207], v[92:95]
	v_mfma_f32_16x16x32_bf16 v[84:87], v[152:155], v[212:215], v[84:87]
	v_mfma_f32_16x16x32_bf16 v[76:79], v[160:163], v[212:215], v[76:79]
	v_mfma_f32_16x16x32_bf16 v[114:117], v[164:167], v[180:183], v[114:117]
	v_mfma_f32_16x16x32_bf16 v[106:109], v[172:175], v[180:183], v[106:109]
	v_mfma_f32_16x16x32_bf16 v[98:101], v[164:167], v[188:191], v[98:101]
	v_mfma_f32_16x16x32_bf16 v[88:91], v[172:175], v[188:191], v[88:91]
	v_mfma_f32_16x16x32_bf16 v[80:83], v[164:167], v[200:203], v[80:83]
	v_mfma_f32_16x16x32_bf16 v[72:75], v[172:175], v[200:203], v[72:75]
	v_mfma_f32_16x16x32_bf16 v[68:71], v[164:167], v[208:211], v[68:71]
	v_mfma_f32_16x16x32_bf16 v[64:67], v[172:175], v[208:211], v[64:67]
	v_mfma_f32_16x16x32_bf16 v[114:117], v[168:171], v[184:187], v[114:117]
	v_mfma_f32_16x16x32_bf16 v[106:109], v[176:179], v[184:187], v[106:109]
	v_mfma_f32_16x16x32_bf16 v[98:101], v[168:171], v[196:199], v[98:101]
	v_mfma_f32_16x16x32_bf16 v[88:91], v[176:179], v[196:199], v[88:91]
	v_mfma_f32_16x16x32_bf16 v[80:83], v[168:171], v[204:207], v[80:83]
	v_mfma_f32_16x16x32_bf16 v[72:75], v[176:179], v[204:207], v[72:75]
	v_mfma_f32_16x16x32_bf16 v[68:71], v[168:171], v[212:215], v[68:71]
	v_mfma_f32_16x16x32_bf16 v[64:67], v[176:179], v[212:215], v[64:67]
	s_setprio 0
	s_barrier
	s_add_i32 s16, s47, s31
	v_lshl_add_u64 v[142:143], v[142:143], 0, s[82:83]
	s_mov_b32 m0, s16
	ds_read_b128 v[180:183], v146 offset:49152
	ds_read_b128 v[184:187], v146 offset:50176
	ds_read_b128 v[188:191], v146 offset:51200
	ds_read_b128 v[196:199], v146 offset:52224
	ds_read_b128 v[200:203], v146 offset:53248
	ds_read_b128 v[204:207], v146 offset:54272
	ds_read_b128 v[208:211], v146 offset:55296
	ds_read_b128 v[212:215], v146 offset:56320
	global_load_lds_dwordx4 v[142:143], off
	s_add_i32 m0, s16, 0x2000
	s_add_u32 s16, s20, 0x160080
	v_lshl_add_u64 v[142:143], v[192:193], 0, s[82:83]
	s_addc_u32 s17, s21, 0
	s_add_i32 s20, s50, s31
	global_load_lds_dwordx4 v[142:143], off
	s_mov_b32 m0, s20
	s_nop 0
	global_load_lds_dwordx4 v132, s[16:17]
	s_add_i32 m0, s20, 0x2000
	s_nop 0
	global_load_lds_dwordx4 v136, s[16:17]
	s_mov_b32 m0, s40
	v_lshl_add_u64 v[142:143], v[216:217], 0, s[82:83]
	global_load_lds_dwordx4 v[142:143], off
	s_mov_b32 m0, s41
	v_lshl_add_u64 v[142:143], v[218:219], 0, s[82:83]
	global_load_lds_dwordx4 v[142:143], off
	s_waitcnt vmcnt(8) lgkmcnt(0)
	s_barrier
	s_setprio 1
	v_mfma_f32_16x16x32_bf16 v[60:63], v[148:151], v[180:183], v[60:63]
	v_mfma_f32_16x16x32_bf16 v[56:59], v[156:159], v[180:183], v[56:59]
	v_mfma_f32_16x16x32_bf16 v[52:55], v[148:151], v[188:191], v[52:55]
	v_mfma_f32_16x16x32_bf16 v[44:47], v[156:159], v[188:191], v[44:47]
	v_mfma_f32_16x16x32_bf16 v[36:39], v[148:151], v[200:203], v[36:39]
	v_mfma_f32_16x16x32_bf16 v[28:31], v[156:159], v[200:203], v[28:31]
	v_mfma_f32_16x16x32_bf16 v[20:23], v[148:151], v[208:211], v[20:23]
	v_mfma_f32_16x16x32_bf16 v[12:15], v[156:159], v[208:211], v[12:15]
	v_mfma_f32_16x16x32_bf16 v[60:63], v[152:155], v[184:187], v[60:63]
	v_mfma_f32_16x16x32_bf16 v[56:59], v[160:163], v[184:187], v[56:59]
	v_mfma_f32_16x16x32_bf16 v[52:55], v[152:155], v[196:199], v[52:55]
	v_mfma_f32_16x16x32_bf16 v[44:47], v[160:163], v[196:199], v[44:47]
	v_mfma_f32_16x16x32_bf16 v[36:39], v[152:155], v[204:207], v[36:39]
	v_mfma_f32_16x16x32_bf16 v[28:31], v[160:163], v[204:207], v[28:31]
	v_mfma_f32_16x16x32_bf16 v[20:23], v[152:155], v[212:215], v[20:23]
	v_mfma_f32_16x16x32_bf16 v[12:15], v[160:163], v[212:215], v[12:15]
	v_mfma_f32_16x16x32_bf16 v[48:51], v[164:167], v[180:183], v[48:51]
	v_mfma_f32_16x16x32_bf16 v[40:43], v[172:175], v[180:183], v[40:43]
	v_mfma_f32_16x16x32_bf16 v[32:35], v[164:167], v[188:191], v[32:35]
	v_mfma_f32_16x16x32_bf16 v[24:27], v[172:175], v[188:191], v[24:27]
	v_mfma_f32_16x16x32_bf16 v[16:19], v[164:167], v[200:203], v[16:19]
	v_mfma_f32_16x16x32_bf16 v[8:11], v[172:175], v[200:203], v[8:11]
	v_mfma_f32_16x16x32_bf16 v[4:7], v[164:167], v[208:211], v[4:7]
	v_mfma_f32_16x16x32_bf16 v[0:3], v[172:175], v[208:211], v[0:3]
	v_mfma_f32_16x16x32_bf16 v[48:51], v[168:171], v[184:187], v[48:51]
	v_mfma_f32_16x16x32_bf16 v[40:43], v[176:179], v[184:187], v[40:43]
	v_mfma_f32_16x16x32_bf16 v[32:35], v[168:171], v[196:199], v[32:35]
	v_mfma_f32_16x16x32_bf16 v[24:27], v[176:179], v[196:199], v[24:27]
	v_mfma_f32_16x16x32_bf16 v[16:19], v[168:171], v[204:207], v[16:19]
	v_mfma_f32_16x16x32_bf16 v[8:11], v[176:179], v[204:207], v[8:11]
	v_mfma_f32_16x16x32_bf16 v[4:7], v[168:171], v[212:215], v[4:7]
	v_mfma_f32_16x16x32_bf16 v[0:3], v[176:179], v[212:215], v[0:3]
	s_setprio 0
	s_barrier
	s_add_u32 s57, s57, 0x100
	s_addc_u32 s58, s58, 0
	s_cmp_ge_i32 s46, s55
	s_mov_b64 s[16:17], s[18:19]
	s_mov_b32 s20, s46
	s_cbranch_scc0 .LBB0_1349
	s_and_b64 vcc, exec, s[10:11]
	s_cbranch_vccz .LBB0_1352
	s_barrier
